# s_setprio 1 raised before the barrier that opens each MFMA segment; redundant lgkmcnt(0) after it deleted; mid-segment setprio pairs deleted
# speedup vs baseline: 1.0081x; 1.0035x over previous
; #define PG8_STAGE(bufoff, gbase, voff) do { _Pragma("unroll") for (int _i = 0; _i < 2; ++_i) \
;         __builtin_amdgcn_global_load_lds((const unsigned*)((const char*)(gbase) + (voff)[_i]), (PG8_LAS unsigned*)(lds + (bufoff) + ldsw + _i * 8192), 16, 0, 0); } while (0)
; #define PG8_LDA(dst, b, h) do { _Pragma("unroll") for (int m = 0; m < 4; ++m) _Pragma("unroll") for (int k = 0; k < 2; ++k) dst[m][k] = *(const PG8_LAS bf16x8*)(lds + PG8_SA(b, h) + aoff + m * 2048 + k * 1024); } while (0)
; #define PG8_LDB(dst, b, h) do { _Pragma("unroll") for (int n = 0; n < 2; ++n) _Pragma("unroll") for (int k = 0; k < 2; ++k) dst[n][k] = *(const PG8_LAS bf16x8*)(lds + PG8_SB(b, h) + boff + n * 2048 + k * 1024); } while (0)
; #define PG8_MMA(ai, bj, At, Bt) do { __builtin_amdgcn_s_setprio(1); _Pragma("unroll") for (int m = 0; m < 4; ++m) _Pragma("unroll") for (int n = 0; n < 2; ++n) _Pragma("unroll") for (int k = 0; k < 2; ++k) \
;         acc[ai][bj][m][n] = __builtin_amdgcn_mfma_f32_16x16x32_bf16(Bt[n][k], At[m][k], acc[ai][bj][m][n], 0, 0, 0); __builtin_amdgcn_s_setprio(0); } while (0)
; #define PG8_WAIT_V(n) asm volatile("s_waitcnt vmcnt(" #n ")" ::: "memory")
; #define PG8_WAIT_L(n) asm volatile("s_waitcnt lgkmcnt(" #n ")" ::: "memory")
; #define PG8_BAR __builtin_amdgcn_s_barrier()
; template <class Epi, class Sched, bool ALIGN_EPI = false, bool SP2 = false>
; __device__ __forceinline__ void gemm_phase(PG8_LAS unsigned char* lds, const Gemm g, const Sched& S, const Epi& E) {
;     ...
;             const char* a1 = cA + (size_t)(t + 1) * kstep;
;             const char* a2 = last ? nA : cA + (size_t)(t + 2) * kstep; const char* b2 = last ? nB : cB + (size_t)(t + 2) * kstep;
;             const char* a3 = a2 + kstep; const char* b3 = b2 + kstep;
;             if (last && has_next) S.a_ready(nxt);
;             if constexpr (SP2) {
;             PG8_LDB(B0, 0, 0); PG8_LDB(B1, 0, 1); PG8_SCHED; PG8_LDA(At, 0, 0); PG8_STAGE(PG8_SA(1, 1), a1 + hstep, voffA);
;             PG8_WAIT_V(8); PG8_WAIT_L(0); PG8_BAR; PG8_MMA(0, 0, At, B0); PG8_MMA(0, 1, At, B1); PG8_BAR; PG8_SCHED;
;             PG8_LDA(At, 0, 1); PG8_STAGE(PG8_SB(0, 0), b2, voffB); PG8_STAGE(PG8_SB(0, 1), b2 + hstep, voffB); PG8_STAGE(PG8_SA(0, 0), a2, voffA);
;             PG8_WAIT_V(8); PG8_WAIT_L(0); PG8_BAR; PG8_MMA(1, 0, At, B0); PG8_MMA(1, 1, At, B1); PG8_BAR; PG8_SCHED;
.LBB0_110:
	s_add_u32 s46, s44, 0xfffc0080
	s_addc_u32 s47, s45, -1
	s_add_i32 s67, 0, 0x10000
	s_cmp_eq_u32 s66, 12
	s_cselect_b32 s49, s17, s47
	s_cselect_b32 s48, s62, s46
	v_add_u32_e32 v145, s67, v143
	s_cselect_b32 s47, s15, s65
	s_cselect_b32 s46, s63, s64
	s_add_i32 s70, 0, 0x14000
	ds_read_b128 v[146:149], v145
	ds_read_b128 v[150:153], v145 offset:1024
	ds_read_b128 v[154:157], v145 offset:2048
	ds_read_b128 v[158:161], v145 offset:3072
	v_add_u32_e32 v145, s70, v143
	ds_read_b128 v[176:179], v145
	ds_read_b128 v[180:183], v145 offset:1024
	ds_read_b128 v[184:187], v145 offset:2048
	ds_read_b128 v[188:191], v145 offset:3072
	v_lshl_add_u64 v[200:201], s[44:45], 0, v[138:139]
	s_add_i32 m0, s50, 0xc000
	ds_read_b128 v[192:195], v144
	ds_read_b128 v[196:199], v144 offset:1024
	ds_read_b128 v[208:211], v144 offset:2048
	ds_read_b128 v[212:215], v144 offset:3072
	ds_read_b128 v[216:219], v144 offset:4096
	ds_read_b128 v[220:223], v144 offset:5120
	ds_read_b128 v[224:227], v144 offset:6144
	ds_read_b128 v[228:231], v144 offset:7168
	global_load_lds_dwordx4 v[200:201], off
	v_lshl_add_u64 v[200:201], s[44:45], 0, v[140:141]
	s_add_i32 m0, s50, 0xe000
	s_nop 0
	global_load_lds_dwordx4 v[200:201], off
	s_waitcnt vmcnt(8)
	s_waitcnt lgkmcnt(0)
	s_setprio 1
	s_barrier
	v_mfma_f32_16x16x32_bf16 v[126:129], v[146:149], v[192:195], v[126:129]
	v_mfma_f32_16x16x32_bf16 v[118:121], v[154:157], v[192:195], v[118:121]
	v_mfma_f32_16x16x32_bf16 v[110:113], v[146:149], v[208:211], v[110:113]
	v_mfma_f32_16x16x32_bf16 v[102:105], v[154:157], v[208:211], v[102:105]
	v_mfma_f32_16x16x32_bf16 v[94:97], v[146:149], v[216:219], v[94:97]
	v_mfma_f32_16x16x32_bf16 v[86:89], v[154:157], v[216:219], v[86:89]
	v_mfma_f32_16x16x32_bf16 v[76:79], v[146:149], v[224:227], v[76:79]
	v_mfma_f32_16x16x32_bf16 v[68:71], v[154:157], v[224:227], v[68:71]
	v_mfma_f32_16x16x32_bf16 v[126:129], v[150:153], v[196:199], v[126:129]
	v_mfma_f32_16x16x32_bf16 v[118:121], v[158:161], v[196:199], v[118:121]
	v_mfma_f32_16x16x32_bf16 v[110:113], v[150:153], v[212:215], v[110:113]
	v_mfma_f32_16x16x32_bf16 v[102:105], v[158:161], v[212:215], v[102:105]
	v_mfma_f32_16x16x32_bf16 v[94:97], v[150:153], v[220:223], v[94:97]
	v_mfma_f32_16x16x32_bf16 v[86:89], v[158:161], v[220:223], v[86:89]
	v_mfma_f32_16x16x32_bf16 v[76:79], v[150:153], v[228:231], v[76:79]
	v_mfma_f32_16x16x32_bf16 v[68:71], v[158:161], v[228:231], v[68:71]
	v_mfma_f32_16x16x32_bf16 v[122:125], v[176:179], v[192:195], v[122:125]
	v_mfma_f32_16x16x32_bf16 v[114:117], v[184:187], v[192:195], v[114:117]
	v_mfma_f32_16x16x32_bf16 v[106:109], v[176:179], v[208:211], v[106:109]
	v_mfma_f32_16x16x32_bf16 v[98:101], v[184:187], v[208:211], v[98:101]
	v_mfma_f32_16x16x32_bf16 v[90:93], v[176:179], v[216:219], v[90:93]
	v_mfma_f32_16x16x32_bf16 v[82:85], v[184:187], v[216:219], v[82:85]
	v_mfma_f32_16x16x32_bf16 v[72:75], v[176:179], v[224:227], v[72:75]
	v_mfma_f32_16x16x32_bf16 v[64:67], v[184:187], v[224:227], v[64:67]
	v_mfma_f32_16x16x32_bf16 v[122:125], v[180:183], v[196:199], v[122:125]
	v_mfma_f32_16x16x32_bf16 v[114:117], v[188:191], v[196:199], v[114:117]
	v_mfma_f32_16x16x32_bf16 v[106:109], v[180:183], v[212:215], v[106:109]
	v_mfma_f32_16x16x32_bf16 v[98:101], v[188:191], v[212:215], v[98:101]
	v_mfma_f32_16x16x32_bf16 v[90:93], v[180:183], v[220:223], v[90:93]
	v_mfma_f32_16x16x32_bf16 v[82:85], v[188:191], v[220:223], v[82:85]
	v_mfma_f32_16x16x32_bf16 v[72:75], v[180:183], v[228:231], v[72:75]
	v_mfma_f32_16x16x32_bf16 v[64:67], v[188:191], v[228:231], v[64:67]
	s_setprio 0
	s_barrier
	s_add_i32 s67, s67, s39
	v_lshl_add_u64 v[200:201], s[46:47], 0, v[134:135]
	s_mov_b32 m0, s67
	ds_read_b128 v[192:195], v144 offset:16384
	ds_read_b128 v[196:199], v144 offset:17408
	ds_read_b128 v[208:211], v144 offset:18432
	ds_read_b128 v[212:215], v144 offset:19456
	ds_read_b128 v[216:219], v144 offset:20480
	ds_read_b128 v[220:223], v144 offset:21504
	ds_read_b128 v[224:227], v144 offset:22528
	ds_read_b128 v[228:231], v144 offset:23552
	global_load_lds_dwordx4 v[200:201], off
	s_add_i32 m0, s67, 0x2000
	s_add_u32 s68, s46, 0x40000
	v_lshl_add_u64 v[232:233], s[46:47], 0, v[130:131]
	s_addc_u32 s69, s47, 0
	s_add_i32 s67, s70, s39
	global_load_lds_dwordx4 v[232:233], off
	v_lshl_add_u64 v[234:235], s[68:69], 0, v[134:135]
	s_mov_b32 m0, s67
	v_lshl_add_u64 v[236:237], s[48:49], 0, v[132:133]
	global_load_lds_dwordx4 v[234:235], off
	v_lshl_add_u64 v[234:235], s[68:69], 0, v[130:131]
	s_add_i32 m0, s67, 0x2000
	s_nop 0
	global_load_lds_dwordx4 v[234:235], off
	v_lshl_add_u64 v[234:235], s[48:49], 0, v[136:137]
	s_mov_b32 m0, s50
	s_nop 0
	global_load_lds_dwordx4 v[234:235], off
	s_mov_b32 m0, s51
	s_nop 0
	global_load_lds_dwordx4 v[236:237], off
	s_waitcnt vmcnt(8)
	s_waitcnt lgkmcnt(0)
	s_setprio 1
	s_barrier
; #define PG8_STAGE(bufoff, gbase, voff) do { _Pragma("unroll") for (int _i = 0; _i < 2; ++_i) \
;         __builtin_amdgcn_global_load_lds((const unsigned*)((const char*)(gbase) + (voff)[_i]), (PG8_LAS unsigned*)(lds + (bufoff) + ldsw + _i * 8192), 16, 0, 0); } while (0)
; #define PG8_LDA(dst, b, h) do { _Pragma("unroll") for (int m = 0; m < 4; ++m) _Pragma("unroll") for (int k = 0; k < 2; ++k) dst[m][k] = *(const PG8_LAS bf16x8*)(lds + PG8_SA(b, h) + aoff + m * 2048 + k * 1024); } while (0)
; #define PG8_LDB(dst, b, h) do { _Pragma("unroll") for (int n = 0; n < 2; ++n) _Pragma("unroll") for (int k = 0; k < 2; ++k) dst[n][k] = *(const PG8_LAS bf16x8*)(lds + PG8_SB(b, h) + boff + n * 2048 + k * 1024); } while (0)
; #define PG8_MMA(ai, bj, At, Bt) do { __builtin_amdgcn_s_setprio(1); _Pragma("unroll") for (int m = 0; m < 4; ++m) _Pragma("unroll") for (int n = 0; n < 2; ++n) _Pragma("unroll") for (int k = 0; k < 2; ++k) \
;         acc[ai][bj][m][n] = __builtin_amdgcn_mfma_f32_16x16x32_bf16(Bt[n][k], At[m][k], acc[ai][bj][m][n], 0, 0, 0); __builtin_amdgcn_s_setprio(0); } while (0)
; #define PG8_WAIT_V(n) asm volatile("s_waitcnt vmcnt(" #n ")" ::: "memory")
; #define PG8_WAIT_L(n) asm volatile("s_waitcnt lgkmcnt(" #n ")" ::: "memory")
; #define PG8_BAR __builtin_amdgcn_s_barrier()
; #define PG8_SCHED __builtin_amdgcn_sched_barrier(0)
; template <class Epi, class Sched, bool ALIGN_EPI = false, bool SP2 = false>
; __device__ __forceinline__ void gemm_phase(PG8_LAS unsigned char* lds, const Gemm g, const Sched& S, const Epi& E) {
;     ...
;             PG8_WAIT_V(8); PG8_WAIT_L(0); PG8_BAR; PG8_MMA(1, 0, At, B0); PG8_MMA(1, 1, At, B1); PG8_BAR; PG8_SCHED;
;             PG8_LDB(B0, 1, 0); PG8_LDB(B1, 1, 1); PG8_SCHED; PG8_LDA(At, 1, 0); PG8_STAGE(PG8_SA(0, 1), a2 + hstep, voffA);
;             PG8_WAIT_V(8); PG8_WAIT_L(0); PG8_BAR; PG8_MMA(0, 0, At, B0); PG8_MMA(0, 1, At, B1); PG8_BAR; PG8_SCHED;
	v_mfma_f32_16x16x32_bf16 v[60:63], v[146:149], v[192:195], v[60:63]
	v_mfma_f32_16x16x32_bf16 v[52:55], v[154:157], v[192:195], v[52:55]
	v_mfma_f32_16x16x32_bf16 v[44:47], v[146:149], v[208:211], v[44:47]
	v_mfma_f32_16x16x32_bf16 v[36:39], v[154:157], v[208:211], v[36:39]
	v_mfma_f32_16x16x32_bf16 v[28:31], v[146:149], v[216:219], v[28:31]
	v_mfma_f32_16x16x32_bf16 v[20:23], v[154:157], v[216:219], v[20:23]
	v_mfma_f32_16x16x32_bf16 v[12:15], v[146:149], v[224:227], v[12:15]
	v_mfma_f32_16x16x32_bf16 v[4:7], v[154:157], v[224:227], v[4:7]
	v_mfma_f32_16x16x32_bf16 v[60:63], v[150:153], v[196:199], v[60:63]
	v_mfma_f32_16x16x32_bf16 v[52:55], v[158:161], v[196:199], v[52:55]
	v_mfma_f32_16x16x32_bf16 v[44:47], v[150:153], v[212:215], v[44:47]
	v_mfma_f32_16x16x32_bf16 v[36:39], v[158:161], v[212:215], v[36:39]
	v_mfma_f32_16x16x32_bf16 v[28:31], v[150:153], v[220:223], v[28:31]
	v_mfma_f32_16x16x32_bf16 v[20:23], v[158:161], v[220:223], v[20:23]
	v_mfma_f32_16x16x32_bf16 v[12:15], v[150:153], v[228:231], v[12:15]
	v_mfma_f32_16x16x32_bf16 v[4:7], v[158:161], v[228:231], v[4:7]
	v_mfma_f32_16x16x32_bf16 v[56:59], v[176:179], v[192:195], v[56:59]
	v_mfma_f32_16x16x32_bf16 v[48:51], v[184:187], v[192:195], v[48:51]
	v_mfma_f32_16x16x32_bf16 v[40:43], v[176:179], v[208:211], v[40:43]
	v_mfma_f32_16x16x32_bf16 v[32:35], v[184:187], v[208:211], v[32:35]
	v_mfma_f32_16x16x32_bf16 v[24:27], v[176:179], v[216:219], v[24:27]
	v_mfma_f32_16x16x32_bf16 v[16:19], v[184:187], v[216:219], v[16:19]
	v_mfma_f32_16x16x32_bf16 v[8:11], v[176:179], v[224:227], v[8:11]
	v_mfma_f32_16x16x32_bf16 v[0:3], v[184:187], v[224:227], v[0:3]
	v_mfma_f32_16x16x32_bf16 v[56:59], v[180:183], v[196:199], v[56:59]
	v_mfma_f32_16x16x32_bf16 v[48:51], v[188:191], v[196:199], v[48:51]
	v_mfma_f32_16x16x32_bf16 v[40:43], v[180:183], v[212:215], v[40:43]
	v_mfma_f32_16x16x32_bf16 v[32:35], v[188:191], v[212:215], v[32:35]
	v_mfma_f32_16x16x32_bf16 v[24:27], v[180:183], v[220:223], v[24:27]
	v_mfma_f32_16x16x32_bf16 v[16:19], v[188:191], v[220:223], v[16:19]
	v_mfma_f32_16x16x32_bf16 v[8:11], v[180:183], v[228:231], v[8:11]
	v_mfma_f32_16x16x32_bf16 v[0:3], v[188:191], v[228:231], v[0:3]
	s_setprio 0
	s_barrier
	s_add_i32 s67, 0, 0x18000
	v_add_u32_e32 v145, s67, v143
	s_add_i32 s68, 0, 0x1c000
	ds_read_b128 v[146:149], v145
	ds_read_b128 v[150:153], v145 offset:1024
	ds_read_b128 v[154:157], v145 offset:2048
	ds_read_b128 v[158:161], v145 offset:3072
	v_add_u32_e32 v145, s68, v143
	ds_read_b128 v[176:179], v145
	ds_read_b128 v[180:183], v145 offset:1024
	ds_read_b128 v[184:187], v145 offset:2048
	ds_read_b128 v[188:191], v145 offset:3072
	s_add_u32 s48, s48, 0x40000
	s_addc_u32 s49, s49, 0
	s_mov_b32 m0, s52
	v_lshl_add_u64 v[238:239], s[48:49], 0, v[136:137]
	ds_read_b128 v[192:195], v144 offset:32768
	ds_read_b128 v[196:199], v144 offset:33792
	ds_read_b128 v[208:211], v144 offset:34816
	ds_read_b128 v[212:215], v144 offset:35840
	ds_read_b128 v[216:219], v144 offset:36864
	ds_read_b128 v[220:223], v144 offset:37888
	ds_read_b128 v[224:227], v144 offset:38912
	ds_read_b128 v[228:231], v144 offset:39936
	global_load_lds_dwordx4 v[238:239], off
	v_lshl_add_u64 v[238:239], s[48:49], 0, v[132:133]
	s_mov_b32 m0, s53
	s_nop 0
	global_load_lds_dwordx4 v[238:239], off
	s_waitcnt vmcnt(8)
	s_waitcnt lgkmcnt(0)
	s_setprio 1
	s_barrier
	v_mfma_f32_16x16x32_bf16 v[126:129], v[146:149], v[192:195], v[126:129]
	v_mfma_f32_16x16x32_bf16 v[118:121], v[154:157], v[192:195], v[118:121]
	v_mfma_f32_16x16x32_bf16 v[110:113], v[146:149], v[208:211], v[110:113]
	v_mfma_f32_16x16x32_bf16 v[102:105], v[154:157], v[208:211], v[102:105]
	v_mfma_f32_16x16x32_bf16 v[94:97], v[146:149], v[216:219], v[94:97]
	v_mfma_f32_16x16x32_bf16 v[86:89], v[154:157], v[216:219], v[86:89]
	v_mfma_f32_16x16x32_bf16 v[76:79], v[146:149], v[224:227], v[76:79]
	v_mfma_f32_16x16x32_bf16 v[68:71], v[154:157], v[224:227], v[68:71]
	v_mfma_f32_16x16x32_bf16 v[126:129], v[150:153], v[196:199], v[126:129]
	v_mfma_f32_16x16x32_bf16 v[118:121], v[158:161], v[196:199], v[118:121]
	v_mfma_f32_16x16x32_bf16 v[110:113], v[150:153], v[212:215], v[110:113]
	v_mfma_f32_16x16x32_bf16 v[102:105], v[158:161], v[212:215], v[102:105]
	v_mfma_f32_16x16x32_bf16 v[94:97], v[150:153], v[220:223], v[94:97]
	v_mfma_f32_16x16x32_bf16 v[86:89], v[158:161], v[220:223], v[86:89]
	v_mfma_f32_16x16x32_bf16 v[76:79], v[150:153], v[228:231], v[76:79]
	v_mfma_f32_16x16x32_bf16 v[68:71], v[158:161], v[228:231], v[68:71]
	v_mfma_f32_16x16x32_bf16 v[122:125], v[176:179], v[192:195], v[122:125]
	v_mfma_f32_16x16x32_bf16 v[114:117], v[184:187], v[192:195], v[114:117]
	v_mfma_f32_16x16x32_bf16 v[106:109], v[176:179], v[208:211], v[106:109]
	v_mfma_f32_16x16x32_bf16 v[98:101], v[184:187], v[208:211], v[98:101]
	v_mfma_f32_16x16x32_bf16 v[90:93], v[176:179], v[216:219], v[90:93]
	v_mfma_f32_16x16x32_bf16 v[82:85], v[184:187], v[216:219], v[82:85]
	v_mfma_f32_16x16x32_bf16 v[72:75], v[176:179], v[224:227], v[72:75]
	v_mfma_f32_16x16x32_bf16 v[64:67], v[184:187], v[224:227], v[64:67]
	v_mfma_f32_16x16x32_bf16 v[122:125], v[180:183], v[196:199], v[122:125]
	v_mfma_f32_16x16x32_bf16 v[114:117], v[188:191], v[196:199], v[114:117]
	v_mfma_f32_16x16x32_bf16 v[106:109], v[180:183], v[212:215], v[106:109]
	v_mfma_f32_16x16x32_bf16 v[98:101], v[188:191], v[212:215], v[98:101]
	v_mfma_f32_16x16x32_bf16 v[90:93], v[180:183], v[220:223], v[90:93]
	v_mfma_f32_16x16x32_bf16 v[82:85], v[188:191], v[220:223], v[82:85]
	v_mfma_f32_16x16x32_bf16 v[72:75], v[180:183], v[228:231], v[72:75]
	v_mfma_f32_16x16x32_bf16 v[64:67], v[188:191], v[228:231], v[64:67]
	s_setprio 0
	s_barrier
; #define PG8_STAGE(bufoff, gbase, voff) do { _Pragma("unroll") for (int _i = 0; _i < 2; ++_i) \
;         __builtin_amdgcn_global_load_lds((const unsigned*)((const char*)(gbase) + (voff)[_i]), (PG8_LAS unsigned*)(lds + (bufoff) + ldsw + _i * 8192), 16, 0, 0); } while (0)
; #define PG8_LDA(dst, b, h) do { _Pragma("unroll") for (int m = 0; m < 4; ++m) _Pragma("unroll") for (int k = 0; k < 2; ++k) dst[m][k] = *(const PG8_LAS bf16x8*)(lds + PG8_SA(b, h) + aoff + m * 2048 + k * 1024); } while (0)
; #define PG8_MMA(ai, bj, At, Bt) do { __builtin_amdgcn_s_setprio(1); _Pragma("unroll") for (int m = 0; m < 4; ++m) _Pragma("unroll") for (int n = 0; n < 2; ++n) _Pragma("unroll") for (int k = 0; k < 2; ++k) \
;         acc[ai][bj][m][n] = __builtin_amdgcn_mfma_f32_16x16x32_bf16(Bt[n][k], At[m][k], acc[ai][bj][m][n], 0, 0, 0); __builtin_amdgcn_s_setprio(0); } while (0)
; #define PG8_WAIT_V(n) asm volatile("s_waitcnt vmcnt(" #n ")" ::: "memory")
; #define PG8_WAIT_L(n) asm volatile("s_waitcnt lgkmcnt(" #n ")" ::: "memory")
; #define PG8_BAR __builtin_amdgcn_s_barrier()
; #define PG8_SCHED __builtin_amdgcn_sched_barrier(0)
; template <class Epi, class Sched, bool ALIGN_EPI = false, bool SP2 = false>
; __device__ __forceinline__ void gemm_phase(PG8_LAS unsigned char* lds, const Gemm g, const Sched& S, const Epi& E) {
;     ...
;             PG8_LDA(At, 1, 1); PG8_STAGE(PG8_SB(1, 0), b3, voffB); PG8_STAGE(PG8_SB(1, 1), b3 + hstep, voffB); PG8_STAGE(PG8_SA(1, 0), a3, voffA);
;             PG8_WAIT_V(8); PG8_WAIT_L(0); PG8_BAR; PG8_MMA(1, 0, At, B0); PG8_MMA(1, 1, At, B1); PG8_BAR; PG8_SCHED;
;     ...
;         if constexpr (ALIGN_EPI) { if (wr == 0) PG8_BAR; }
	s_add_i32 s48, s67, s39
	v_lshl_add_u64 v[200:201], v[200:201], 0, s[40:41]
	s_mov_b32 m0, s48
	ds_read_b128 v[192:195], v144 offset:49152
	ds_read_b128 v[196:199], v144 offset:50176
	ds_read_b128 v[208:211], v144 offset:51200
	ds_read_b128 v[212:215], v144 offset:52224
	ds_read_b128 v[216:219], v144 offset:53248
	ds_read_b128 v[220:223], v144 offset:54272
	ds_read_b128 v[224:227], v144 offset:55296
	ds_read_b128 v[228:231], v144 offset:56320
	global_load_lds_dwordx4 v[200:201], off
	s_add_i32 m0, s48, 0x2000
	s_add_u32 s46, s46, 0x40080
	v_lshl_add_u64 v[200:201], v[232:233], 0, s[40:41]
	s_addc_u32 s47, s47, 0
	s_add_i32 s48, s68, s39
	global_load_lds_dwordx4 v[200:201], off
	v_lshl_add_u64 v[200:201], s[46:47], 0, v[134:135]
	s_mov_b32 m0, s48
	s_nop 0
	global_load_lds_dwordx4 v[200:201], off
	v_lshl_add_u64 v[200:201], s[46:47], 0, v[130:131]
	s_add_i32 m0, s48, 0x2000
	s_nop 0
	global_load_lds_dwordx4 v[200:201], off
	v_lshl_add_u64 v[200:201], v[234:235], 0, s[40:41]
	s_mov_b32 m0, s56
	s_nop 0
	global_load_lds_dwordx4 v[200:201], off
	v_lshl_add_u64 v[200:201], v[236:237], 0, s[40:41]
	s_mov_b32 m0, s57
	s_nop 0
	global_load_lds_dwordx4 v[200:201], off
	s_waitcnt vmcnt(8)
	s_waitcnt lgkmcnt(0)
	s_setprio 1
	s_barrier
	v_mfma_f32_16x16x32_bf16 v[60:63], v[146:149], v[192:195], v[60:63]
	v_mfma_f32_16x16x32_bf16 v[52:55], v[154:157], v[192:195], v[52:55]
	v_mfma_f32_16x16x32_bf16 v[44:47], v[146:149], v[208:211], v[44:47]
	v_mfma_f32_16x16x32_bf16 v[36:39], v[154:157], v[208:211], v[36:39]
	v_mfma_f32_16x16x32_bf16 v[28:31], v[146:149], v[216:219], v[28:31]
	v_mfma_f32_16x16x32_bf16 v[20:23], v[154:157], v[216:219], v[20:23]
	v_mfma_f32_16x16x32_bf16 v[12:15], v[146:149], v[224:227], v[12:15]
	v_mfma_f32_16x16x32_bf16 v[4:7], v[154:157], v[224:227], v[4:7]
	v_mfma_f32_16x16x32_bf16 v[60:63], v[150:153], v[196:199], v[60:63]
	v_mfma_f32_16x16x32_bf16 v[52:55], v[158:161], v[196:199], v[52:55]
	v_mfma_f32_16x16x32_bf16 v[44:47], v[150:153], v[212:215], v[44:47]
	v_mfma_f32_16x16x32_bf16 v[36:39], v[158:161], v[212:215], v[36:39]
	v_mfma_f32_16x16x32_bf16 v[28:31], v[150:153], v[220:223], v[28:31]
	v_mfma_f32_16x16x32_bf16 v[20:23], v[158:161], v[220:223], v[20:23]
	v_mfma_f32_16x16x32_bf16 v[12:15], v[150:153], v[228:231], v[12:15]
	v_mfma_f32_16x16x32_bf16 v[4:7], v[158:161], v[228:231], v[4:7]
	v_mfma_f32_16x16x32_bf16 v[56:59], v[176:179], v[192:195], v[56:59]
	v_mfma_f32_16x16x32_bf16 v[48:51], v[184:187], v[192:195], v[48:51]
	v_mfma_f32_16x16x32_bf16 v[40:43], v[176:179], v[208:211], v[40:43]
	v_mfma_f32_16x16x32_bf16 v[32:35], v[184:187], v[208:211], v[32:35]
	v_mfma_f32_16x16x32_bf16 v[24:27], v[176:179], v[216:219], v[24:27]
	v_mfma_f32_16x16x32_bf16 v[16:19], v[184:187], v[216:219], v[16:19]
	v_mfma_f32_16x16x32_bf16 v[8:11], v[176:179], v[224:227], v[8:11]
	v_mfma_f32_16x16x32_bf16 v[0:3], v[184:187], v[224:227], v[0:3]
	v_mfma_f32_16x16x32_bf16 v[56:59], v[180:183], v[196:199], v[56:59]
	v_mfma_f32_16x16x32_bf16 v[48:51], v[188:191], v[196:199], v[48:51]
	v_mfma_f32_16x16x32_bf16 v[40:43], v[180:183], v[212:215], v[40:43]
	v_mfma_f32_16x16x32_bf16 v[32:35], v[188:191], v[212:215], v[32:35]
	v_mfma_f32_16x16x32_bf16 v[24:27], v[180:183], v[220:223], v[24:27]
	v_mfma_f32_16x16x32_bf16 v[16:19], v[188:191], v[220:223], v[16:19]
	v_mfma_f32_16x16x32_bf16 v[8:11], v[180:183], v[228:231], v[8:11]
	v_mfma_f32_16x16x32_bf16 v[0:3], v[188:191], v[228:231], v[0:3]
	s_setprio 0
	s_barrier
	s_add_i32 s66, s66, 2
	s_add_u32 s44, s44, 0x100
	s_addc_u32 s45, s45, 0
	s_add_u32 s64, s64, 0x100
	s_addc_u32 s65, s65, 0
	s_cmp_gt_u32 s66, 13
	s_cbranch_scc0 .LBB0_110
	s_and_b64 vcc, exec, s[12:13]
	s_cbranch_vccz .LBB0_113
	s_barrier

; #define PG8_STAGE(bufoff, gbase, voff) do { _Pragma("unroll") for (int _i = 0; _i < 2; ++_i) \
;         __builtin_amdgcn_global_load_lds((const unsigned*)((const char*)(gbase) + (voff)[_i]), (PG8_LAS unsigned*)(lds + (bufoff) + ldsw + _i * 8192), 16, 0, 0); } while (0)
; #define PG8_LDA(dst, b, h) do { _Pragma("unroll") for (int m = 0; m < 4; ++m) _Pragma("unroll") for (int k = 0; k < 2; ++k) dst[m][k] = *(const PG8_LAS bf16x8*)(lds + PG8_SA(b, h) + aoff + m * 2048 + k * 1024); } while (0)
; #define PG8_LDB(dst, b, h) do { _Pragma("unroll") for (int n = 0; n < 2; ++n) _Pragma("unroll") for (int k = 0; k < 2; ++k) dst[n][k] = *(const PG8_LAS bf16x8*)(lds + PG8_SB(b, h) + boff + n * 2048 + k * 1024); } while (0)
; #define PG8_MMA(ai, bj, At, Bt) do { __builtin_amdgcn_s_setprio(1); _Pragma("unroll") for (int m = 0; m < 4; ++m) _Pragma("unroll") for (int n = 0; n < 2; ++n) _Pragma("unroll") for (int k = 0; k < 2; ++k) \
;         acc[ai][bj][m][n] = __builtin_amdgcn_mfma_f32_16x16x32_bf16(Bt[n][k], At[m][k], acc[ai][bj][m][n], 0, 0, 0); __builtin_amdgcn_s_setprio(0); } while (0)
; #define PG8_WAIT_V(n) asm volatile("s_waitcnt vmcnt(" #n ")" ::: "memory")
; #define PG8_WAIT_L(n) asm volatile("s_waitcnt lgkmcnt(" #n ")" ::: "memory")
; #define PG8_BAR __builtin_amdgcn_s_barrier()
; template <class Epi, class Sched, bool ALIGN_EPI = false, bool SP2 = false>
; __device__ __forceinline__ void gemm_phase(PG8_LAS unsigned char* lds, const Gemm g, const Sched& S, const Epi& E) {
;     ...
;             const char* a1 = cA + (size_t)(t + 1) * kstep;
;             const char* a2 = last ? nA : cA + (size_t)(t + 2) * kstep; const char* b2 = last ? nB : cB + (size_t)(t + 2) * kstep;
;             const char* a3 = a2 + kstep; const char* b3 = b2 + kstep;
;             if (last && has_next) S.a_ready(nxt);
;             if constexpr (SP2) {
;             PG8_LDB(B0, 0, 0); PG8_LDB(B1, 0, 1); PG8_SCHED; PG8_LDA(At, 0, 0); PG8_STAGE(PG8_SA(1, 1), a1 + hstep, voffA);
;             PG8_WAIT_V(8); PG8_WAIT_L(0); PG8_BAR; PG8_MMA(0, 0, At, B0); PG8_MMA(0, 1, At, B1); PG8_BAR; PG8_SCHED;
;             PG8_LDA(At, 0, 1); PG8_STAGE(PG8_SB(0, 0), b2, voffB); PG8_STAGE(PG8_SB(0, 1), b2 + hstep, voffB); PG8_STAGE(PG8_SA(0, 0), a2, voffA);
;             PG8_WAIT_V(8); PG8_WAIT_L(0); PG8_BAR; PG8_MMA(1, 0, At, B0); PG8_MMA(1, 1, At, B1); PG8_BAR; PG8_SCHED;
.LBB0_129:
	s_add_u32 s48, s46, 0xfffc0080
	s_addc_u32 s49, s47, -1
	s_add_i32 s69, 0, 0x10000
	s_cmp_eq_u32 s68, 12
	s_cselect_b32 s51, s19, s49
	s_cselect_b32 s50, s64, s48
	v_add_u32_e32 v142, s69, v148
	s_cselect_b32 s49, s17, s67
	s_cselect_b32 s48, s65, s66
	s_add_i32 s72, 0, 0x14000
	ds_read_b128 v[150:153], v142
	ds_read_b128 v[154:157], v142 offset:1024
	ds_read_b128 v[158:161], v142 offset:2048
	ds_read_b128 v[176:179], v142 offset:3072
	v_add_u32_e32 v142, s72, v148
	ds_read_b128 v[180:183], v142
	ds_read_b128 v[184:187], v142 offset:1024
	ds_read_b128 v[188:191], v142 offset:2048
	ds_read_b128 v[192:195], v142 offset:3072
	v_lshl_add_u64 v[142:143], s[46:47], 0, v[138:139]
	s_add_i32 m0, s53, 0xc000
	ds_read_b128 v[196:199], v149
	ds_read_b128 v[208:211], v149 offset:1024
	ds_read_b128 v[212:215], v149 offset:2048
	ds_read_b128 v[216:219], v149 offset:3072
	ds_read_b128 v[220:223], v149 offset:4096
	ds_read_b128 v[224:227], v149 offset:5120
	ds_read_b128 v[228:231], v149 offset:6144
	ds_read_b128 v[232:235], v149 offset:7168
	global_load_lds_dwordx4 v[142:143], off
	v_lshl_add_u64 v[142:143], s[46:47], 0, v[140:141]
	s_add_i32 m0, s53, 0xe000
	s_nop 0
	global_load_lds_dwordx4 v[142:143], off
	s_waitcnt vmcnt(8)
	s_waitcnt lgkmcnt(0)
	s_setprio 1
	s_barrier
	v_mfma_f32_16x16x32_bf16 v[126:129], v[150:153], v[196:199], v[126:129]
	v_mfma_f32_16x16x32_bf16 v[122:125], v[158:161], v[196:199], v[122:125]
	v_mfma_f32_16x16x32_bf16 v[114:117], v[150:153], v[212:215], v[114:117]
	v_mfma_f32_16x16x32_bf16 v[106:109], v[158:161], v[212:215], v[106:109]
	v_mfma_f32_16x16x32_bf16 v[98:101], v[150:153], v[220:223], v[98:101]
	v_mfma_f32_16x16x32_bf16 v[90:93], v[158:161], v[220:223], v[90:93]
	v_mfma_f32_16x16x32_bf16 v[82:85], v[150:153], v[228:231], v[82:85]
	v_mfma_f32_16x16x32_bf16 v[72:75], v[158:161], v[228:231], v[72:75]
	v_mfma_f32_16x16x32_bf16 v[126:129], v[154:157], v[208:211], v[126:129]
	v_mfma_f32_16x16x32_bf16 v[122:125], v[176:179], v[208:211], v[122:125]
	v_mfma_f32_16x16x32_bf16 v[114:117], v[154:157], v[216:219], v[114:117]
	v_mfma_f32_16x16x32_bf16 v[106:109], v[176:179], v[216:219], v[106:109]
	v_mfma_f32_16x16x32_bf16 v[98:101], v[154:157], v[224:227], v[98:101]
	v_mfma_f32_16x16x32_bf16 v[90:93], v[176:179], v[224:227], v[90:93]
	v_mfma_f32_16x16x32_bf16 v[82:85], v[154:157], v[232:235], v[82:85]
	v_mfma_f32_16x16x32_bf16 v[72:75], v[176:179], v[232:235], v[72:75]
	v_mfma_f32_16x16x32_bf16 v[118:121], v[180:183], v[196:199], v[118:121]
	v_mfma_f32_16x16x32_bf16 v[110:113], v[188:191], v[196:199], v[110:113]
	v_mfma_f32_16x16x32_bf16 v[102:105], v[180:183], v[212:215], v[102:105]
	v_mfma_f32_16x16x32_bf16 v[94:97], v[188:191], v[212:215], v[94:97]
	v_mfma_f32_16x16x32_bf16 v[86:89], v[180:183], v[220:223], v[86:89]
	v_mfma_f32_16x16x32_bf16 v[76:79], v[188:191], v[220:223], v[76:79]
	v_mfma_f32_16x16x32_bf16 v[68:71], v[180:183], v[228:231], v[68:71]
	v_mfma_f32_16x16x32_bf16 v[64:67], v[188:191], v[228:231], v[64:67]
	v_mfma_f32_16x16x32_bf16 v[118:121], v[184:187], v[208:211], v[118:121]
	v_mfma_f32_16x16x32_bf16 v[110:113], v[192:195], v[208:211], v[110:113]
	v_mfma_f32_16x16x32_bf16 v[102:105], v[184:187], v[216:219], v[102:105]
	v_mfma_f32_16x16x32_bf16 v[94:97], v[192:195], v[216:219], v[94:97]
	v_mfma_f32_16x16x32_bf16 v[86:89], v[184:187], v[224:227], v[86:89]
	v_mfma_f32_16x16x32_bf16 v[76:79], v[192:195], v[224:227], v[76:79]
	v_mfma_f32_16x16x32_bf16 v[68:71], v[184:187], v[232:235], v[68:71]
	v_mfma_f32_16x16x32_bf16 v[64:67], v[192:195], v[232:235], v[64:67]
	s_setprio 0
	s_barrier
	s_add_i32 s69, s69, s52
	v_lshl_add_u64 v[142:143], s[48:49], 0, v[134:135]
	s_mov_b32 m0, s69
	ds_read_b128 v[196:199], v149 offset:16384
	ds_read_b128 v[208:211], v149 offset:17408
	ds_read_b128 v[212:215], v149 offset:18432
	ds_read_b128 v[216:219], v149 offset:19456
	ds_read_b128 v[220:223], v149 offset:20480
	ds_read_b128 v[224:227], v149 offset:21504
	ds_read_b128 v[228:231], v149 offset:22528
	ds_read_b128 v[232:235], v149 offset:23552
	global_load_lds_dwordx4 v[142:143], off
	s_add_i32 m0, s69, 0x2000
	s_add_u32 s70, s48, 0x40000
	v_lshl_add_u64 v[146:147], s[48:49], 0, v[130:131]
	s_addc_u32 s71, s49, 0
	s_add_i32 s69, s72, s52
	global_load_lds_dwordx4 v[146:147], off
	v_lshl_add_u64 v[200:201], s[70:71], 0, v[134:135]
	s_mov_b32 m0, s69
	v_lshl_add_u64 v[236:237], s[50:51], 0, v[132:133]
	global_load_lds_dwordx4 v[200:201], off
	v_lshl_add_u64 v[200:201], s[70:71], 0, v[130:131]
	s_add_i32 m0, s69, 0x2000
	s_nop 0
	global_load_lds_dwordx4 v[200:201], off
	v_lshl_add_u64 v[200:201], s[50:51], 0, v[136:137]
	s_mov_b32 m0, s53
	s_nop 0
	global_load_lds_dwordx4 v[200:201], off
	s_mov_b32 m0, s54
	s_nop 0
	global_load_lds_dwordx4 v[236:237], off
	s_waitcnt vmcnt(8)
	s_waitcnt lgkmcnt(0)
	s_setprio 1
	s_barrier
; #define PG8_STAGE(bufoff, gbase, voff) do { _Pragma("unroll") for (int _i = 0; _i < 2; ++_i) \
;         __builtin_amdgcn_global_load_lds((const unsigned*)((const char*)(gbase) + (voff)[_i]), (PG8_LAS unsigned*)(lds + (bufoff) + ldsw + _i * 8192), 16, 0, 0); } while (0)
; #define PG8_LDA(dst, b, h) do { _Pragma("unroll") for (int m = 0; m < 4; ++m) _Pragma("unroll") for (int k = 0; k < 2; ++k) dst[m][k] = *(const PG8_LAS bf16x8*)(lds + PG8_SA(b, h) + aoff + m * 2048 + k * 1024); } while (0)
; #define PG8_LDB(dst, b, h) do { _Pragma("unroll") for (int n = 0; n < 2; ++n) _Pragma("unroll") for (int k = 0; k < 2; ++k) dst[n][k] = *(const PG8_LAS bf16x8*)(lds + PG8_SB(b, h) + boff + n * 2048 + k * 1024); } while (0)
; #define PG8_MMA(ai, bj, At, Bt) do { __builtin_amdgcn_s_setprio(1); _Pragma("unroll") for (int m = 0; m < 4; ++m) _Pragma("unroll") for (int n = 0; n < 2; ++n) _Pragma("unroll") for (int k = 0; k < 2; ++k) \
;         acc[ai][bj][m][n] = __builtin_amdgcn_mfma_f32_16x16x32_bf16(Bt[n][k], At[m][k], acc[ai][bj][m][n], 0, 0, 0); __builtin_amdgcn_s_setprio(0); } while (0)
; #define PG8_WAIT_V(n) asm volatile("s_waitcnt vmcnt(" #n ")" ::: "memory")
; #define PG8_WAIT_L(n) asm volatile("s_waitcnt lgkmcnt(" #n ")" ::: "memory")
; #define PG8_BAR __builtin_amdgcn_s_barrier()
; #define PG8_SCHED __builtin_amdgcn_sched_barrier(0)
; template <class Epi, class Sched, bool ALIGN_EPI = false, bool SP2 = false>
; __device__ __forceinline__ void gemm_phase(PG8_LAS unsigned char* lds, const Gemm g, const Sched& S, const Epi& E) {
;     ...
;             PG8_WAIT_V(8); PG8_WAIT_L(0); PG8_BAR; PG8_MMA(1, 0, At, B0); PG8_MMA(1, 1, At, B1); PG8_BAR; PG8_SCHED;
;             PG8_LDB(B0, 1, 0); PG8_LDB(B1, 1, 1); PG8_SCHED; PG8_LDA(At, 1, 0); PG8_STAGE(PG8_SA(0, 1), a2 + hstep, voffA);
;             PG8_WAIT_V(8); PG8_WAIT_L(0); PG8_BAR; PG8_MMA(0, 0, At, B0); PG8_MMA(0, 1, At, B1); PG8_BAR; PG8_SCHED;
	v_mfma_f32_16x16x32_bf16 v[60:63], v[150:153], v[196:199], v[60:63]
	v_mfma_f32_16x16x32_bf16 v[56:59], v[158:161], v[196:199], v[56:59]
	v_mfma_f32_16x16x32_bf16 v[48:51], v[150:153], v[212:215], v[48:51]
	v_mfma_f32_16x16x32_bf16 v[40:43], v[158:161], v[212:215], v[40:43]
	v_mfma_f32_16x16x32_bf16 v[32:35], v[150:153], v[220:223], v[32:35]
	v_mfma_f32_16x16x32_bf16 v[24:27], v[158:161], v[220:223], v[24:27]
	v_mfma_f32_16x16x32_bf16 v[16:19], v[150:153], v[228:231], v[16:19]
	v_mfma_f32_16x16x32_bf16 v[8:11], v[158:161], v[228:231], v[8:11]
	v_mfma_f32_16x16x32_bf16 v[60:63], v[154:157], v[208:211], v[60:63]
	v_mfma_f32_16x16x32_bf16 v[56:59], v[176:179], v[208:211], v[56:59]
	v_mfma_f32_16x16x32_bf16 v[48:51], v[154:157], v[216:219], v[48:51]
	v_mfma_f32_16x16x32_bf16 v[40:43], v[176:179], v[216:219], v[40:43]
	v_mfma_f32_16x16x32_bf16 v[32:35], v[154:157], v[224:227], v[32:35]
	v_mfma_f32_16x16x32_bf16 v[24:27], v[176:179], v[224:227], v[24:27]
	v_mfma_f32_16x16x32_bf16 v[16:19], v[154:157], v[232:235], v[16:19]
	v_mfma_f32_16x16x32_bf16 v[8:11], v[176:179], v[232:235], v[8:11]
	v_mfma_f32_16x16x32_bf16 v[52:55], v[180:183], v[196:199], v[52:55]
	v_mfma_f32_16x16x32_bf16 v[44:47], v[188:191], v[196:199], v[44:47]
	v_mfma_f32_16x16x32_bf16 v[36:39], v[180:183], v[212:215], v[36:39]
	v_mfma_f32_16x16x32_bf16 v[28:31], v[188:191], v[212:215], v[28:31]
	v_mfma_f32_16x16x32_bf16 v[20:23], v[180:183], v[220:223], v[20:23]
	v_mfma_f32_16x16x32_bf16 v[12:15], v[188:191], v[220:223], v[12:15]
	v_mfma_f32_16x16x32_bf16 v[4:7], v[180:183], v[228:231], v[4:7]
	v_mfma_f32_16x16x32_bf16 v[0:3], v[188:191], v[228:231], v[0:3]
	v_mfma_f32_16x16x32_bf16 v[52:55], v[184:187], v[208:211], v[52:55]
	v_mfma_f32_16x16x32_bf16 v[44:47], v[192:195], v[208:211], v[44:47]
	v_mfma_f32_16x16x32_bf16 v[36:39], v[184:187], v[216:219], v[36:39]
	v_mfma_f32_16x16x32_bf16 v[28:31], v[192:195], v[216:219], v[28:31]
	v_mfma_f32_16x16x32_bf16 v[20:23], v[184:187], v[224:227], v[20:23]
	v_mfma_f32_16x16x32_bf16 v[12:15], v[192:195], v[224:227], v[12:15]
	v_mfma_f32_16x16x32_bf16 v[4:7], v[184:187], v[232:235], v[4:7]
	v_mfma_f32_16x16x32_bf16 v[0:3], v[192:195], v[232:235], v[0:3]
	s_setprio 0
	s_barrier
	s_add_i32 s69, 0, 0x18000
	v_add_u32_e32 v144, s69, v148
	s_add_i32 s70, 0, 0x1c000
	ds_read_b128 v[150:153], v144
	ds_read_b128 v[154:157], v144 offset:1024
	ds_read_b128 v[158:161], v144 offset:2048
	ds_read_b128 v[176:179], v144 offset:3072
	v_add_u32_e32 v144, s70, v148
	ds_read_b128 v[180:183], v144
	ds_read_b128 v[184:187], v144 offset:1024
	ds_read_b128 v[188:191], v144 offset:2048
	ds_read_b128 v[192:195], v144 offset:3072
	s_add_u32 s50, s50, 0x40000
	s_addc_u32 s51, s51, 0
	s_mov_b32 m0, s55
	v_lshl_add_u64 v[238:239], s[50:51], 0, v[136:137]
	ds_read_b128 v[196:199], v149 offset:32768
	ds_read_b128 v[208:211], v149 offset:33792
	ds_read_b128 v[212:215], v149 offset:34816
	ds_read_b128 v[216:219], v149 offset:35840
	ds_read_b128 v[220:223], v149 offset:36864
	ds_read_b128 v[224:227], v149 offset:37888
	ds_read_b128 v[228:231], v149 offset:38912
	ds_read_b128 v[232:235], v149 offset:39936
	global_load_lds_dwordx4 v[238:239], off
	v_lshl_add_u64 v[238:239], s[50:51], 0, v[132:133]
	s_mov_b32 m0, s56
	s_nop 0
	global_load_lds_dwordx4 v[238:239], off
	s_waitcnt vmcnt(8)
	s_waitcnt lgkmcnt(0)
	s_setprio 1
	s_barrier
	v_mfma_f32_16x16x32_bf16 v[126:129], v[150:153], v[196:199], v[126:129]
	v_mfma_f32_16x16x32_bf16 v[122:125], v[158:161], v[196:199], v[122:125]
	v_mfma_f32_16x16x32_bf16 v[114:117], v[150:153], v[212:215], v[114:117]
	v_mfma_f32_16x16x32_bf16 v[106:109], v[158:161], v[212:215], v[106:109]
	v_mfma_f32_16x16x32_bf16 v[98:101], v[150:153], v[220:223], v[98:101]
	v_mfma_f32_16x16x32_bf16 v[90:93], v[158:161], v[220:223], v[90:93]
	v_mfma_f32_16x16x32_bf16 v[82:85], v[150:153], v[228:231], v[82:85]
	v_mfma_f32_16x16x32_bf16 v[72:75], v[158:161], v[228:231], v[72:75]
	v_mfma_f32_16x16x32_bf16 v[126:129], v[154:157], v[208:211], v[126:129]
	v_mfma_f32_16x16x32_bf16 v[122:125], v[176:179], v[208:211], v[122:125]
	v_mfma_f32_16x16x32_bf16 v[114:117], v[154:157], v[216:219], v[114:117]
	v_mfma_f32_16x16x32_bf16 v[106:109], v[176:179], v[216:219], v[106:109]
	v_mfma_f32_16x16x32_bf16 v[98:101], v[154:157], v[224:227], v[98:101]
	v_mfma_f32_16x16x32_bf16 v[90:93], v[176:179], v[224:227], v[90:93]
	v_mfma_f32_16x16x32_bf16 v[82:85], v[154:157], v[232:235], v[82:85]
	v_mfma_f32_16x16x32_bf16 v[72:75], v[176:179], v[232:235], v[72:75]
	v_mfma_f32_16x16x32_bf16 v[118:121], v[180:183], v[196:199], v[118:121]
	v_mfma_f32_16x16x32_bf16 v[110:113], v[188:191], v[196:199], v[110:113]
	v_mfma_f32_16x16x32_bf16 v[102:105], v[180:183], v[212:215], v[102:105]
	v_mfma_f32_16x16x32_bf16 v[94:97], v[188:191], v[212:215], v[94:97]
	v_mfma_f32_16x16x32_bf16 v[86:89], v[180:183], v[220:223], v[86:89]
	v_mfma_f32_16x16x32_bf16 v[76:79], v[188:191], v[220:223], v[76:79]
	v_mfma_f32_16x16x32_bf16 v[68:71], v[180:183], v[228:231], v[68:71]
	v_mfma_f32_16x16x32_bf16 v[64:67], v[188:191], v[228:231], v[64:67]
	v_mfma_f32_16x16x32_bf16 v[118:121], v[184:187], v[208:211], v[118:121]
	v_mfma_f32_16x16x32_bf16 v[110:113], v[192:195], v[208:211], v[110:113]
	v_mfma_f32_16x16x32_bf16 v[102:105], v[184:187], v[216:219], v[102:105]
	v_mfma_f32_16x16x32_bf16 v[94:97], v[192:195], v[216:219], v[94:97]
	v_mfma_f32_16x16x32_bf16 v[86:89], v[184:187], v[224:227], v[86:89]
	v_mfma_f32_16x16x32_bf16 v[76:79], v[192:195], v[224:227], v[76:79]
	v_mfma_f32_16x16x32_bf16 v[68:71], v[184:187], v[232:235], v[68:71]
	v_mfma_f32_16x16x32_bf16 v[64:67], v[192:195], v[232:235], v[64:67]
	s_setprio 0
	s_barrier
; #define PG8_STAGE(bufoff, gbase, voff) do { _Pragma("unroll") for (int _i = 0; _i < 2; ++_i) \
;         __builtin_amdgcn_global_load_lds((const unsigned*)((const char*)(gbase) + (voff)[_i]), (PG8_LAS unsigned*)(lds + (bufoff) + ldsw + _i * 8192), 16, 0, 0); } while (0)
; #define PG8_LDA(dst, b, h) do { _Pragma("unroll") for (int m = 0; m < 4; ++m) _Pragma("unroll") for (int k = 0; k < 2; ++k) dst[m][k] = *(const PG8_LAS bf16x8*)(lds + PG8_SA(b, h) + aoff + m * 2048 + k * 1024); } while (0)
; #define PG8_MMA(ai, bj, At, Bt) do { __builtin_amdgcn_s_setprio(1); _Pragma("unroll") for (int m = 0; m < 4; ++m) _Pragma("unroll") for (int n = 0; n < 2; ++n) _Pragma("unroll") for (int k = 0; k < 2; ++k) \
;         acc[ai][bj][m][n] = __builtin_amdgcn_mfma_f32_16x16x32_bf16(Bt[n][k], At[m][k], acc[ai][bj][m][n], 0, 0, 0); __builtin_amdgcn_s_setprio(0); } while (0)
; #define PG8_WAIT_V(n) asm volatile("s_waitcnt vmcnt(" #n ")" ::: "memory")
; #define PG8_WAIT_L(n) asm volatile("s_waitcnt lgkmcnt(" #n ")" ::: "memory")
; #define PG8_BAR __builtin_amdgcn_s_barrier()
; #define PG8_SCHED __builtin_amdgcn_sched_barrier(0)
; template <class Epi, class Sched, bool ALIGN_EPI = false, bool SP2 = false>
; __device__ __forceinline__ void gemm_phase(PG8_LAS unsigned char* lds, const Gemm g, const Sched& S, const Epi& E) {
;     ...
;             PG8_LDA(At, 1, 1); PG8_STAGE(PG8_SB(1, 0), b3, voffB); PG8_STAGE(PG8_SB(1, 1), b3 + hstep, voffB); PG8_STAGE(PG8_SA(1, 0), a3, voffA);
;             PG8_WAIT_V(8); PG8_WAIT_L(0); PG8_BAR; PG8_MMA(1, 0, At, B0); PG8_MMA(1, 1, At, B1); PG8_BAR; PG8_SCHED;
;     ...
;         if constexpr (ALIGN_EPI) { if (wr == 0) PG8_BAR; }
	s_add_i32 s50, s69, s52
	v_lshl_add_u64 v[142:143], v[142:143], 0, s[40:41]
	s_mov_b32 m0, s50
	ds_read_b128 v[196:199], v149 offset:49152
	ds_read_b128 v[208:211], v149 offset:50176
	ds_read_b128 v[212:215], v149 offset:51200
	ds_read_b128 v[216:219], v149 offset:52224
	ds_read_b128 v[220:223], v149 offset:53248
	ds_read_b128 v[224:227], v149 offset:54272
	ds_read_b128 v[228:231], v149 offset:55296
	ds_read_b128 v[232:235], v149 offset:56320
	global_load_lds_dwordx4 v[142:143], off
	s_add_i32 m0, s50, 0x2000
	s_add_u32 s48, s48, 0x40080
	v_lshl_add_u64 v[142:143], v[146:147], 0, s[40:41]
	s_addc_u32 s49, s49, 0
	s_add_i32 s50, s70, s52
	global_load_lds_dwordx4 v[142:143], off
	v_lshl_add_u64 v[142:143], s[48:49], 0, v[134:135]
	s_mov_b32 m0, s50
	s_nop 0
	global_load_lds_dwordx4 v[142:143], off
	v_lshl_add_u64 v[142:143], s[48:49], 0, v[130:131]
	s_add_i32 m0, s50, 0x2000
	s_nop 0
	global_load_lds_dwordx4 v[142:143], off
	v_lshl_add_u64 v[142:143], v[200:201], 0, s[40:41]
	s_mov_b32 m0, s59
	s_nop 0
	global_load_lds_dwordx4 v[142:143], off
	v_lshl_add_u64 v[142:143], v[236:237], 0, s[40:41]
	s_mov_b32 m0, s60
	s_nop 0
	global_load_lds_dwordx4 v[142:143], off
	s_waitcnt vmcnt(8)
	s_waitcnt lgkmcnt(0)
	s_setprio 1
	s_barrier
	v_mfma_f32_16x16x32_bf16 v[60:63], v[150:153], v[196:199], v[60:63]
	v_mfma_f32_16x16x32_bf16 v[56:59], v[158:161], v[196:199], v[56:59]
	v_mfma_f32_16x16x32_bf16 v[48:51], v[150:153], v[212:215], v[48:51]
	v_mfma_f32_16x16x32_bf16 v[40:43], v[158:161], v[212:215], v[40:43]
	v_mfma_f32_16x16x32_bf16 v[32:35], v[150:153], v[220:223], v[32:35]
	v_mfma_f32_16x16x32_bf16 v[24:27], v[158:161], v[220:223], v[24:27]
	v_mfma_f32_16x16x32_bf16 v[16:19], v[150:153], v[228:231], v[16:19]
	v_mfma_f32_16x16x32_bf16 v[8:11], v[158:161], v[228:231], v[8:11]
	v_mfma_f32_16x16x32_bf16 v[60:63], v[154:157], v[208:211], v[60:63]
	v_mfma_f32_16x16x32_bf16 v[56:59], v[176:179], v[208:211], v[56:59]
	v_mfma_f32_16x16x32_bf16 v[48:51], v[154:157], v[216:219], v[48:51]
	v_mfma_f32_16x16x32_bf16 v[40:43], v[176:179], v[216:219], v[40:43]
	v_mfma_f32_16x16x32_bf16 v[32:35], v[154:157], v[224:227], v[32:35]
	v_mfma_f32_16x16x32_bf16 v[24:27], v[176:179], v[224:227], v[24:27]
	v_mfma_f32_16x16x32_bf16 v[16:19], v[154:157], v[232:235], v[16:19]
	v_mfma_f32_16x16x32_bf16 v[8:11], v[176:179], v[232:235], v[8:11]
	v_mfma_f32_16x16x32_bf16 v[52:55], v[180:183], v[196:199], v[52:55]
	v_mfma_f32_16x16x32_bf16 v[44:47], v[188:191], v[196:199], v[44:47]
	v_mfma_f32_16x16x32_bf16 v[36:39], v[180:183], v[212:215], v[36:39]
	v_mfma_f32_16x16x32_bf16 v[28:31], v[188:191], v[212:215], v[28:31]
	v_mfma_f32_16x16x32_bf16 v[20:23], v[180:183], v[220:223], v[20:23]
	v_mfma_f32_16x16x32_bf16 v[12:15], v[188:191], v[220:223], v[12:15]
	v_mfma_f32_16x16x32_bf16 v[4:7], v[180:183], v[228:231], v[4:7]
	v_mfma_f32_16x16x32_bf16 v[0:3], v[188:191], v[228:231], v[0:3]
	v_mfma_f32_16x16x32_bf16 v[52:55], v[184:187], v[208:211], v[52:55]
	v_mfma_f32_16x16x32_bf16 v[44:47], v[192:195], v[208:211], v[44:47]
	v_mfma_f32_16x16x32_bf16 v[36:39], v[184:187], v[216:219], v[36:39]
	v_mfma_f32_16x16x32_bf16 v[28:31], v[192:195], v[216:219], v[28:31]
	v_mfma_f32_16x16x32_bf16 v[20:23], v[184:187], v[224:227], v[20:23]
	v_mfma_f32_16x16x32_bf16 v[12:15], v[192:195], v[224:227], v[12:15]
	v_mfma_f32_16x16x32_bf16 v[4:7], v[184:187], v[232:235], v[4:7]
	v_mfma_f32_16x16x32_bf16 v[0:3], v[192:195], v[232:235], v[0:3]
	s_setprio 0
	s_barrier
	s_add_i32 s68, s68, 2
	s_add_u32 s46, s46, 0x100
	s_addc_u32 s47, s47, 0
	s_add_u32 s66, s66, 0x100
	s_addc_u32 s67, s67, 0
	s_cmp_gt_u32 s68, 13
	s_cbranch_scc0 .LBB0_129
	s_and_b64 vcc, exec, s[14:15]
	s_cbranch_vccz .LBB0_132
	s_barrier

; #define PG8_STAGE(bufoff, gbase, voff) do { _Pragma("unroll") for (int _i = 0; _i < 2; ++_i) \
;         __builtin_amdgcn_global_load_lds((const unsigned*)((const char*)(gbase) + (voff)[_i]), (PG8_LAS unsigned*)(lds + (bufoff) + ldsw + _i * 8192), 16, 0, 0); } while (0)
; #define PG8_LDA(dst, b, h) do { _Pragma("unroll") for (int m = 0; m < 4; ++m) _Pragma("unroll") for (int k = 0; k < 2; ++k) dst[m][k] = *(const PG8_LAS bf16x8*)(lds + PG8_SA(b, h) + aoff + m * 2048 + k * 1024); } while (0)
; #define PG8_LDB(dst, b, h) do { _Pragma("unroll") for (int n = 0; n < 2; ++n) _Pragma("unroll") for (int k = 0; k < 2; ++k) dst[n][k] = *(const PG8_LAS bf16x8*)(lds + PG8_SB(b, h) + boff + n * 2048 + k * 1024); } while (0)
; #define PG8_MMA(ai, bj, At, Bt) do { __builtin_amdgcn_s_setprio(1); _Pragma("unroll") for (int m = 0; m < 4; ++m) _Pragma("unroll") for (int n = 0; n < 2; ++n) _Pragma("unroll") for (int k = 0; k < 2; ++k) \
;         acc[ai][bj][m][n] = __builtin_amdgcn_mfma_f32_16x16x32_bf16(Bt[n][k], At[m][k], acc[ai][bj][m][n], 0, 0, 0); __builtin_amdgcn_s_setprio(0); } while (0)
; #define PG8_WAIT_V(n) asm volatile("s_waitcnt vmcnt(" #n ")" ::: "memory")
; #define PG8_WAIT_L(n) asm volatile("s_waitcnt lgkmcnt(" #n ")" ::: "memory")
; template <class Epi, class Sched, bool ALIGN_EPI = false, bool SP2 = false>
; __device__ __forceinline__ void gemm_phase(PG8_LAS unsigned char* lds, const Gemm g, const Sched& S, const Epi& E) {
;     ...
;             const bool last = (t == nt - 2);
;             const char* a1 = cA + (size_t)(t + 1) * kstep;
;             const char* a2 = last ? nA : cA + (size_t)(t + 2) * kstep; const char* b2 = last ? nB : cB + (size_t)(t + 2) * kstep;
;             const char* a3 = a2 + kstep; const char* b3 = b2 + kstep;
;             if (last && has_next) S.a_ready(nxt);
;             if constexpr (SP2) {
;             PG8_LDB(B0, 0, 0); PG8_LDB(B1, 0, 1); PG8_SCHED; PG8_LDA(At, 0, 0); PG8_STAGE(PG8_SA(1, 1), a1 + hstep, voffA);
;             PG8_WAIT_V(8); PG8_WAIT_L(0); PG8_BAR; PG8_MMA(0, 0, At, B0); PG8_MMA(0, 1, At, B1); PG8_BAR; PG8_SCHED;
;             PG8_LDA(At, 0, 1); PG8_STAGE(PG8_SB(0, 0), b2, voffB); PG8_STAGE(PG8_SB(0, 1), b2 + hstep, voffB); PG8_STAGE(PG8_SA(0, 0), a2, voffA);
;             PG8_WAIT_V(8); PG8_WAIT_L(0); PG8_BAR; PG8_MMA(1, 0, At, B0); PG8_MMA(1, 1, At, B1); PG8_BAR; PG8_SCHED;
.LBB0_159:
	s_add_u32 s48, s6, 0xfffc0080
	s_addc_u32 s49, s7, -1
	s_add_i32 s71, 0, 0x10000
	s_cmp_eq_u32 s70, 12
	s_cselect_b32 s51, s5, s49
	s_cselect_b32 s50, s17, s48
	s_cselect_b32 s49, s19, s69
	s_cselect_b32 s48, s67, s68
	s_add_i32 s74, 0, 0x14000
	v_add_u32_e32 v142, s71, v199
	v_add_u32_e32 v158, s74, v199
	ds_read_b128 v[130:133], v142
	ds_read_b128 v[134:137], v142 offset:1024
	ds_read_b128 v[138:141], v142 offset:2048
	s_waitcnt lgkmcnt(0)
	ds_read_b128 v[142:145], v142 offset:3072
	ds_read_b128 v[146:149], v158
	ds_read_b128 v[150:153], v158 offset:1024
	ds_read_b128 v[154:157], v158 offset:2048
	ds_read_b128 v[158:161], v158 offset:3072
	v_lshl_add_u64 v[196:197], s[6:7], 0, v[184:185]
	s_add_i32 m0, s11, 0xc000
	ds_read_b128 v[188:191], v200
	ds_read_b128 v[192:195], v200 offset:1024
	ds_read_b128 v[208:211], v200 offset:2048
	ds_read_b128 v[212:215], v200 offset:3072
	ds_read_b128 v[216:219], v200 offset:4096
	ds_read_b128 v[220:223], v200 offset:5120
	ds_read_b128 v[224:227], v200 offset:6144
	ds_read_b128 v[228:231], v200 offset:7168
	global_load_lds_dwordx4 v[196:197], off
	v_lshl_add_u64 v[196:197], s[6:7], 0, v[186:187]
	s_add_i32 m0, s11, 0xe000
	s_nop 0
	global_load_lds_dwordx4 v[196:197], off
	s_waitcnt vmcnt(8)
	s_waitcnt lgkmcnt(0)
	s_setprio 1
	s_barrier
	v_mfma_f32_16x16x32_bf16 v[126:129], v[130:133], v[188:191], v[126:129]
	v_mfma_f32_16x16x32_bf16 v[122:125], v[138:141], v[188:191], v[122:125]
	v_mfma_f32_16x16x32_bf16 v[110:113], v[130:133], v[208:211], v[110:113]
	v_mfma_f32_16x16x32_bf16 v[106:109], v[138:141], v[208:211], v[106:109]
	v_mfma_f32_16x16x32_bf16 v[94:97], v[130:133], v[216:219], v[94:97]
	v_mfma_f32_16x16x32_bf16 v[90:93], v[138:141], v[216:219], v[90:93]
	v_mfma_f32_16x16x32_bf16 v[76:79], v[130:133], v[224:227], v[76:79]
	v_mfma_f32_16x16x32_bf16 v[72:75], v[138:141], v[224:227], v[72:75]
	v_mfma_f32_16x16x32_bf16 v[126:129], v[134:137], v[192:195], v[126:129]
	v_mfma_f32_16x16x32_bf16 v[122:125], v[142:145], v[192:195], v[122:125]
	v_mfma_f32_16x16x32_bf16 v[110:113], v[134:137], v[212:215], v[110:113]
	v_mfma_f32_16x16x32_bf16 v[106:109], v[142:145], v[212:215], v[106:109]
	v_mfma_f32_16x16x32_bf16 v[94:97], v[134:137], v[220:223], v[94:97]
	v_mfma_f32_16x16x32_bf16 v[90:93], v[142:145], v[220:223], v[90:93]
	v_mfma_f32_16x16x32_bf16 v[76:79], v[134:137], v[228:231], v[76:79]
	v_mfma_f32_16x16x32_bf16 v[72:75], v[142:145], v[228:231], v[72:75]
	v_mfma_f32_16x16x32_bf16 v[118:121], v[146:149], v[188:191], v[118:121]
	v_mfma_f32_16x16x32_bf16 v[114:117], v[154:157], v[188:191], v[114:117]
	v_mfma_f32_16x16x32_bf16 v[102:105], v[146:149], v[208:211], v[102:105]
	v_mfma_f32_16x16x32_bf16 v[98:101], v[154:157], v[208:211], v[98:101]
	v_mfma_f32_16x16x32_bf16 v[86:89], v[146:149], v[216:219], v[86:89]
	v_mfma_f32_16x16x32_bf16 v[82:85], v[154:157], v[216:219], v[82:85]
	v_mfma_f32_16x16x32_bf16 v[68:71], v[146:149], v[224:227], v[68:71]
	v_mfma_f32_16x16x32_bf16 v[64:67], v[154:157], v[224:227], v[64:67]
	v_mfma_f32_16x16x32_bf16 v[118:121], v[150:153], v[192:195], v[118:121]
	v_mfma_f32_16x16x32_bf16 v[114:117], v[158:161], v[192:195], v[114:117]
	v_mfma_f32_16x16x32_bf16 v[102:105], v[150:153], v[212:215], v[102:105]
	v_mfma_f32_16x16x32_bf16 v[98:101], v[158:161], v[212:215], v[98:101]
	v_mfma_f32_16x16x32_bf16 v[86:89], v[150:153], v[220:223], v[86:89]
	v_mfma_f32_16x16x32_bf16 v[82:85], v[158:161], v[220:223], v[82:85]
	v_mfma_f32_16x16x32_bf16 v[68:71], v[150:153], v[228:231], v[68:71]
	v_mfma_f32_16x16x32_bf16 v[64:67], v[158:161], v[228:231], v[64:67]
	s_setprio 0
	s_barrier
	s_add_i32 s71, s71, s54
	v_lshl_add_u64 v[196:197], s[48:49], 0, v[178:179]
	s_mov_b32 m0, s71
	ds_read_b128 v[188:191], v200 offset:16384
	ds_read_b128 v[192:195], v200 offset:17408
	ds_read_b128 v[208:211], v200 offset:18432
	ds_read_b128 v[212:215], v200 offset:19456
	ds_read_b128 v[216:219], v200 offset:20480
	ds_read_b128 v[220:223], v200 offset:21504
	ds_read_b128 v[224:227], v200 offset:22528
	ds_read_b128 v[228:231], v200 offset:23552
	global_load_lds_dwordx4 v[196:197], off
	s_add_i32 m0, s71, 0x2000
	s_add_u32 s72, s48, 0x40000
	v_lshl_add_u64 v[232:233], s[48:49], 0, v[182:183]
	s_addc_u32 s73, s49, 0
	s_add_i32 s71, s74, s54
	global_load_lds_dwordx4 v[232:233], off
	v_lshl_add_u64 v[234:235], s[72:73], 0, v[178:179]
	s_mov_b32 m0, s71
	v_lshl_add_u64 v[236:237], s[50:51], 0, v[180:181]
	global_load_lds_dwordx4 v[234:235], off
	v_lshl_add_u64 v[234:235], s[72:73], 0, v[182:183]
	s_add_i32 m0, s71, 0x2000
	s_nop 0
	global_load_lds_dwordx4 v[234:235], off
	v_lshl_add_u64 v[234:235], s[50:51], 0, v[176:177]
	s_mov_b32 m0, s11
	s_nop 0
	global_load_lds_dwordx4 v[234:235], off
	s_mov_b32 m0, s55
	s_nop 0
	global_load_lds_dwordx4 v[236:237], off
	s_waitcnt vmcnt(8)
	s_waitcnt lgkmcnt(0)
	s_setprio 1
	s_barrier
; #define PG8_STAGE(bufoff, gbase, voff) do { _Pragma("unroll") for (int _i = 0; _i < 2; ++_i) \
;         __builtin_amdgcn_global_load_lds((const unsigned*)((const char*)(gbase) + (voff)[_i]), (PG8_LAS unsigned*)(lds + (bufoff) + ldsw + _i * 8192), 16, 0, 0); } while (0)
; #define PG8_LDA(dst, b, h) do { _Pragma("unroll") for (int m = 0; m < 4; ++m) _Pragma("unroll") for (int k = 0; k < 2; ++k) dst[m][k] = *(const PG8_LAS bf16x8*)(lds + PG8_SA(b, h) + aoff + m * 2048 + k * 1024); } while (0)
; #define PG8_LDB(dst, b, h) do { _Pragma("unroll") for (int n = 0; n < 2; ++n) _Pragma("unroll") for (int k = 0; k < 2; ++k) dst[n][k] = *(const PG8_LAS bf16x8*)(lds + PG8_SB(b, h) + boff + n * 2048 + k * 1024); } while (0)
; #define PG8_MMA(ai, bj, At, Bt) do { __builtin_amdgcn_s_setprio(1); _Pragma("unroll") for (int m = 0; m < 4; ++m) _Pragma("unroll") for (int n = 0; n < 2; ++n) _Pragma("unroll") for (int k = 0; k < 2; ++k) \
;         acc[ai][bj][m][n] = __builtin_amdgcn_mfma_f32_16x16x32_bf16(Bt[n][k], At[m][k], acc[ai][bj][m][n], 0, 0, 0); __builtin_amdgcn_s_setprio(0); } while (0)
; #define PG8_WAIT_V(n) asm volatile("s_waitcnt vmcnt(" #n ")" ::: "memory")
; #define PG8_WAIT_L(n) asm volatile("s_waitcnt lgkmcnt(" #n ")" ::: "memory")
; #define PG8_BAR __builtin_amdgcn_s_barrier()
; #define PG8_SCHED __builtin_amdgcn_sched_barrier(0)
; template <class Epi, class Sched, bool ALIGN_EPI = false, bool SP2 = false>
; __device__ __forceinline__ void gemm_phase(PG8_LAS unsigned char* lds, const Gemm g, const Sched& S, const Epi& E) {
;     ...
;             PG8_WAIT_V(8); PG8_WAIT_L(0); PG8_BAR; PG8_MMA(1, 0, At, B0); PG8_MMA(1, 1, At, B1); PG8_BAR; PG8_SCHED;
;             PG8_LDB(B0, 1, 0); PG8_LDB(B1, 1, 1); PG8_SCHED; PG8_LDA(At, 1, 0); PG8_STAGE(PG8_SA(0, 1), a2 + hstep, voffA);
;             PG8_WAIT_V(8); PG8_WAIT_L(0); PG8_BAR; PG8_MMA(0, 0, At, B0); PG8_MMA(0, 1, At, B1); PG8_BAR; PG8_SCHED;
	v_mfma_f32_16x16x32_bf16 v[60:63], v[130:133], v[188:191], v[60:63]
	v_mfma_f32_16x16x32_bf16 v[56:59], v[138:141], v[188:191], v[56:59]
	v_mfma_f32_16x16x32_bf16 v[44:47], v[130:133], v[208:211], v[44:47]
	v_mfma_f32_16x16x32_bf16 v[40:43], v[138:141], v[208:211], v[40:43]
	v_mfma_f32_16x16x32_bf16 v[28:31], v[130:133], v[216:219], v[28:31]
	v_mfma_f32_16x16x32_bf16 v[24:27], v[138:141], v[216:219], v[24:27]
	v_mfma_f32_16x16x32_bf16 v[12:15], v[130:133], v[224:227], v[12:15]
	v_mfma_f32_16x16x32_bf16 v[8:11], v[138:141], v[224:227], v[8:11]
	v_mfma_f32_16x16x32_bf16 v[60:63], v[134:137], v[192:195], v[60:63]
	v_mfma_f32_16x16x32_bf16 v[56:59], v[142:145], v[192:195], v[56:59]
	v_mfma_f32_16x16x32_bf16 v[44:47], v[134:137], v[212:215], v[44:47]
	v_mfma_f32_16x16x32_bf16 v[40:43], v[142:145], v[212:215], v[40:43]
	v_mfma_f32_16x16x32_bf16 v[28:31], v[134:137], v[220:223], v[28:31]
	v_mfma_f32_16x16x32_bf16 v[24:27], v[142:145], v[220:223], v[24:27]
	v_mfma_f32_16x16x32_bf16 v[12:15], v[134:137], v[228:231], v[12:15]
	v_mfma_f32_16x16x32_bf16 v[8:11], v[142:145], v[228:231], v[8:11]
	v_mfma_f32_16x16x32_bf16 v[52:55], v[146:149], v[188:191], v[52:55]
	v_mfma_f32_16x16x32_bf16 v[48:51], v[154:157], v[188:191], v[48:51]
	v_mfma_f32_16x16x32_bf16 v[36:39], v[146:149], v[208:211], v[36:39]
	v_mfma_f32_16x16x32_bf16 v[32:35], v[154:157], v[208:211], v[32:35]
	v_mfma_f32_16x16x32_bf16 v[20:23], v[146:149], v[216:219], v[20:23]
	v_mfma_f32_16x16x32_bf16 v[16:19], v[154:157], v[216:219], v[16:19]
	v_mfma_f32_16x16x32_bf16 v[4:7], v[146:149], v[224:227], v[4:7]
	v_mfma_f32_16x16x32_bf16 v[0:3], v[154:157], v[224:227], v[0:3]
	v_mfma_f32_16x16x32_bf16 v[52:55], v[150:153], v[192:195], v[52:55]
	v_mfma_f32_16x16x32_bf16 v[48:51], v[158:161], v[192:195], v[48:51]
	v_mfma_f32_16x16x32_bf16 v[36:39], v[150:153], v[212:215], v[36:39]
	v_mfma_f32_16x16x32_bf16 v[32:35], v[158:161], v[212:215], v[32:35]
	v_mfma_f32_16x16x32_bf16 v[20:23], v[150:153], v[220:223], v[20:23]
	v_mfma_f32_16x16x32_bf16 v[16:19], v[158:161], v[220:223], v[16:19]
	v_mfma_f32_16x16x32_bf16 v[4:7], v[150:153], v[228:231], v[4:7]
	v_mfma_f32_16x16x32_bf16 v[0:3], v[158:161], v[228:231], v[0:3]
	s_setprio 0
	s_barrier
	s_add_i32 s71, 0, 0x18000
	s_add_i32 s72, 0, 0x1c000
	v_add_u32_e32 v142, s71, v199
	v_add_u32_e32 v158, s72, v199
	ds_read_b128 v[130:133], v142
	ds_read_b128 v[134:137], v142 offset:1024
	ds_read_b128 v[138:141], v142 offset:2048
	ds_read_b128 v[142:145], v142 offset:3072
	ds_read_b128 v[146:149], v158
	ds_read_b128 v[150:153], v158 offset:1024
	ds_read_b128 v[154:157], v158 offset:2048
	ds_read_b128 v[158:161], v158 offset:3072
	s_add_u32 s50, s50, 0x40000
	s_addc_u32 s51, s51, 0
	s_mov_b32 m0, s56
	v_lshl_add_u64 v[238:239], s[50:51], 0, v[176:177]
	ds_read_b128 v[188:191], v200 offset:32768
	ds_read_b128 v[192:195], v200 offset:33792
	ds_read_b128 v[208:211], v200 offset:34816
	ds_read_b128 v[212:215], v200 offset:35840
	ds_read_b128 v[216:219], v200 offset:36864
	ds_read_b128 v[220:223], v200 offset:37888
	ds_read_b128 v[224:227], v200 offset:38912
	ds_read_b128 v[228:231], v200 offset:39936
	global_load_lds_dwordx4 v[238:239], off
	v_lshl_add_u64 v[238:239], s[50:51], 0, v[180:181]
	s_mov_b32 m0, s57
	s_nop 0
	global_load_lds_dwordx4 v[238:239], off
	s_waitcnt vmcnt(8)
	s_waitcnt lgkmcnt(0)
	s_setprio 1
	s_barrier
	v_mfma_f32_16x16x32_bf16 v[126:129], v[130:133], v[188:191], v[126:129]
	v_mfma_f32_16x16x32_bf16 v[122:125], v[138:141], v[188:191], v[122:125]
	v_mfma_f32_16x16x32_bf16 v[110:113], v[130:133], v[208:211], v[110:113]
	v_mfma_f32_16x16x32_bf16 v[106:109], v[138:141], v[208:211], v[106:109]
	v_mfma_f32_16x16x32_bf16 v[94:97], v[130:133], v[216:219], v[94:97]
	v_mfma_f32_16x16x32_bf16 v[90:93], v[138:141], v[216:219], v[90:93]
	v_mfma_f32_16x16x32_bf16 v[76:79], v[130:133], v[224:227], v[76:79]
	v_mfma_f32_16x16x32_bf16 v[72:75], v[138:141], v[224:227], v[72:75]
	v_mfma_f32_16x16x32_bf16 v[126:129], v[134:137], v[192:195], v[126:129]
	v_mfma_f32_16x16x32_bf16 v[122:125], v[142:145], v[192:195], v[122:125]
	v_mfma_f32_16x16x32_bf16 v[110:113], v[134:137], v[212:215], v[110:113]
	v_mfma_f32_16x16x32_bf16 v[106:109], v[142:145], v[212:215], v[106:109]
	v_mfma_f32_16x16x32_bf16 v[94:97], v[134:137], v[220:223], v[94:97]
	v_mfma_f32_16x16x32_bf16 v[90:93], v[142:145], v[220:223], v[90:93]
	v_mfma_f32_16x16x32_bf16 v[76:79], v[134:137], v[228:231], v[76:79]
	v_mfma_f32_16x16x32_bf16 v[72:75], v[142:145], v[228:231], v[72:75]
	v_mfma_f32_16x16x32_bf16 v[118:121], v[146:149], v[188:191], v[118:121]
	v_mfma_f32_16x16x32_bf16 v[114:117], v[154:157], v[188:191], v[114:117]
	v_mfma_f32_16x16x32_bf16 v[102:105], v[146:149], v[208:211], v[102:105]
	v_mfma_f32_16x16x32_bf16 v[98:101], v[154:157], v[208:211], v[98:101]
	v_mfma_f32_16x16x32_bf16 v[86:89], v[146:149], v[216:219], v[86:89]
	v_mfma_f32_16x16x32_bf16 v[82:85], v[154:157], v[216:219], v[82:85]
	v_mfma_f32_16x16x32_bf16 v[68:71], v[146:149], v[224:227], v[68:71]
	v_mfma_f32_16x16x32_bf16 v[64:67], v[154:157], v[224:227], v[64:67]
	v_mfma_f32_16x16x32_bf16 v[118:121], v[150:153], v[192:195], v[118:121]
	v_mfma_f32_16x16x32_bf16 v[114:117], v[158:161], v[192:195], v[114:117]
	v_mfma_f32_16x16x32_bf16 v[102:105], v[150:153], v[212:215], v[102:105]
	v_mfma_f32_16x16x32_bf16 v[98:101], v[158:161], v[212:215], v[98:101]
	v_mfma_f32_16x16x32_bf16 v[86:89], v[150:153], v[220:223], v[86:89]
	v_mfma_f32_16x16x32_bf16 v[82:85], v[158:161], v[220:223], v[82:85]
	v_mfma_f32_16x16x32_bf16 v[68:71], v[150:153], v[228:231], v[68:71]
	v_mfma_f32_16x16x32_bf16 v[64:67], v[158:161], v[228:231], v[64:67]
	s_setprio 0
	s_barrier
; #define PG8_STAGE(bufoff, gbase, voff) do { _Pragma("unroll") for (int _i = 0; _i < 2; ++_i) \
;         __builtin_amdgcn_global_load_lds((const unsigned*)((const char*)(gbase) + (voff)[_i]), (PG8_LAS unsigned*)(lds + (bufoff) + ldsw + _i * 8192), 16, 0, 0); } while (0)
; #define PG8_LDA(dst, b, h) do { _Pragma("unroll") for (int m = 0; m < 4; ++m) _Pragma("unroll") for (int k = 0; k < 2; ++k) dst[m][k] = *(const PG8_LAS bf16x8*)(lds + PG8_SA(b, h) + aoff + m * 2048 + k * 1024); } while (0)
; #define PG8_MMA(ai, bj, At, Bt) do { __builtin_amdgcn_s_setprio(1); _Pragma("unroll") for (int m = 0; m < 4; ++m) _Pragma("unroll") for (int n = 0; n < 2; ++n) _Pragma("unroll") for (int k = 0; k < 2; ++k) \
;         acc[ai][bj][m][n] = __builtin_amdgcn_mfma_f32_16x16x32_bf16(Bt[n][k], At[m][k], acc[ai][bj][m][n], 0, 0, 0); __builtin_amdgcn_s_setprio(0); } while (0)
; #define PG8_WAIT_V(n) asm volatile("s_waitcnt vmcnt(" #n ")" ::: "memory")
; #define PG8_WAIT_L(n) asm volatile("s_waitcnt lgkmcnt(" #n ")" ::: "memory")
; #define PG8_BAR __builtin_amdgcn_s_barrier()
; #define PG8_SCHED __builtin_amdgcn_sched_barrier(0)
; template <class Epi, class Sched, bool ALIGN_EPI = false, bool SP2 = false>
; __device__ __forceinline__ void gemm_phase(PG8_LAS unsigned char* lds, const Gemm g, const Sched& S, const Epi& E) {
;     ...
;             PG8_LDA(At, 1, 1); PG8_STAGE(PG8_SB(1, 0), b3, voffB); PG8_STAGE(PG8_SB(1, 1), b3 + hstep, voffB); PG8_STAGE(PG8_SA(1, 0), a3, voffA);
;             PG8_WAIT_V(8); PG8_WAIT_L(0); PG8_BAR; PG8_MMA(1, 0, At, B0); PG8_MMA(1, 1, At, B1); PG8_BAR; PG8_SCHED;
;     ...
;         if constexpr (ALIGN_EPI) { if (wr == 0) PG8_BAR; }
	s_add_i32 s50, s71, s54
	v_lshl_add_u64 v[196:197], v[196:197], 0, s[40:41]
	s_mov_b32 m0, s50
	ds_read_b128 v[188:191], v200 offset:49152
	ds_read_b128 v[192:195], v200 offset:50176
	ds_read_b128 v[208:211], v200 offset:51200
	ds_read_b128 v[212:215], v200 offset:52224
	ds_read_b128 v[216:219], v200 offset:53248
	ds_read_b128 v[220:223], v200 offset:54272
	ds_read_b128 v[224:227], v200 offset:55296
	ds_read_b128 v[228:231], v200 offset:56320
	global_load_lds_dwordx4 v[196:197], off
	s_add_i32 m0, s50, 0x2000
	s_add_u32 s48, s48, 0x40080
	v_lshl_add_u64 v[196:197], v[232:233], 0, s[40:41]
	s_addc_u32 s49, s49, 0
	s_add_i32 s50, s72, s54
	global_load_lds_dwordx4 v[196:197], off
	v_lshl_add_u64 v[196:197], s[48:49], 0, v[178:179]
	s_mov_b32 m0, s50
	s_nop 0
	global_load_lds_dwordx4 v[196:197], off
	v_lshl_add_u64 v[196:197], s[48:49], 0, v[182:183]
	s_add_i32 m0, s50, 0x2000
	s_nop 0
	global_load_lds_dwordx4 v[196:197], off
	v_lshl_add_u64 v[196:197], v[234:235], 0, s[40:41]
	s_mov_b32 m0, s61
	s_nop 0
	global_load_lds_dwordx4 v[196:197], off
	v_lshl_add_u64 v[196:197], v[236:237], 0, s[40:41]
	s_mov_b32 m0, s62
	s_nop 0
	global_load_lds_dwordx4 v[196:197], off
	s_waitcnt vmcnt(8)
	s_waitcnt lgkmcnt(0)
	s_setprio 1
	s_barrier
	v_mfma_f32_16x16x32_bf16 v[60:63], v[130:133], v[188:191], v[60:63]
	v_mfma_f32_16x16x32_bf16 v[56:59], v[138:141], v[188:191], v[56:59]
	v_mfma_f32_16x16x32_bf16 v[44:47], v[130:133], v[208:211], v[44:47]
	v_mfma_f32_16x16x32_bf16 v[40:43], v[138:141], v[208:211], v[40:43]
	v_mfma_f32_16x16x32_bf16 v[28:31], v[130:133], v[216:219], v[28:31]
	v_mfma_f32_16x16x32_bf16 v[24:27], v[138:141], v[216:219], v[24:27]
	v_mfma_f32_16x16x32_bf16 v[12:15], v[130:133], v[224:227], v[12:15]
	v_mfma_f32_16x16x32_bf16 v[8:11], v[138:141], v[224:227], v[8:11]
	v_mfma_f32_16x16x32_bf16 v[60:63], v[134:137], v[192:195], v[60:63]
	v_mfma_f32_16x16x32_bf16 v[56:59], v[142:145], v[192:195], v[56:59]
	v_mfma_f32_16x16x32_bf16 v[44:47], v[134:137], v[212:215], v[44:47]
	v_mfma_f32_16x16x32_bf16 v[40:43], v[142:145], v[212:215], v[40:43]
	v_mfma_f32_16x16x32_bf16 v[28:31], v[134:137], v[220:223], v[28:31]
	v_mfma_f32_16x16x32_bf16 v[24:27], v[142:145], v[220:223], v[24:27]
	v_mfma_f32_16x16x32_bf16 v[12:15], v[134:137], v[228:231], v[12:15]
	v_mfma_f32_16x16x32_bf16 v[8:11], v[142:145], v[228:231], v[8:11]
	v_mfma_f32_16x16x32_bf16 v[52:55], v[146:149], v[188:191], v[52:55]
	v_mfma_f32_16x16x32_bf16 v[48:51], v[154:157], v[188:191], v[48:51]
	v_mfma_f32_16x16x32_bf16 v[36:39], v[146:149], v[208:211], v[36:39]
	v_mfma_f32_16x16x32_bf16 v[32:35], v[154:157], v[208:211], v[32:35]
	v_mfma_f32_16x16x32_bf16 v[20:23], v[146:149], v[216:219], v[20:23]
	v_mfma_f32_16x16x32_bf16 v[16:19], v[154:157], v[216:219], v[16:19]
	v_mfma_f32_16x16x32_bf16 v[4:7], v[146:149], v[224:227], v[4:7]
	v_mfma_f32_16x16x32_bf16 v[0:3], v[154:157], v[224:227], v[0:3]
	v_mfma_f32_16x16x32_bf16 v[52:55], v[150:153], v[192:195], v[52:55]
	v_mfma_f32_16x16x32_bf16 v[48:51], v[158:161], v[192:195], v[48:51]
	v_mfma_f32_16x16x32_bf16 v[36:39], v[150:153], v[212:215], v[36:39]
	v_mfma_f32_16x16x32_bf16 v[32:35], v[158:161], v[212:215], v[32:35]
	v_mfma_f32_16x16x32_bf16 v[20:23], v[150:153], v[220:223], v[20:23]
	v_mfma_f32_16x16x32_bf16 v[16:19], v[158:161], v[220:223], v[16:19]
	v_mfma_f32_16x16x32_bf16 v[4:7], v[150:153], v[228:231], v[4:7]
	v_mfma_f32_16x16x32_bf16 v[0:3], v[158:161], v[228:231], v[0:3]
	s_setprio 0
	s_barrier
	s_add_i32 s70, s70, 2
	s_add_u32 s6, s6, 0x100
	s_addc_u32 s7, s7, 0
	s_add_u32 s68, s68, 0x100
	s_addc_u32 s69, s69, 0
	s_cmp_gt_u32 s70, 13
	s_cbranch_scc0 .LBB0_159
	s_and_b64 vcc, exec, s[14:15]
	s_cbranch_vccz .LBB0_162
	s_barrier

; #define PG8_STAGE(bufoff, gbase, voff) do { _Pragma("unroll") for (int _i = 0; _i < 2; ++_i) \
;         __builtin_amdgcn_global_load_lds((const unsigned*)((const char*)(gbase) + (voff)[_i]), (PG8_LAS unsigned*)(lds + (bufoff) + ldsw + _i * 8192), 16, 0, 0); } while (0)
; #define PG8_LDA(dst, b, h) do { _Pragma("unroll") for (int m = 0; m < 4; ++m) _Pragma("unroll") for (int k = 0; k < 2; ++k) dst[m][k] = *(const PG8_LAS bf16x8*)(lds + PG8_SA(b, h) + aoff + m * 2048 + k * 1024); } while (0)
; #define PG8_LDB(dst, b, h) do { _Pragma("unroll") for (int n = 0; n < 2; ++n) _Pragma("unroll") for (int k = 0; k < 2; ++k) dst[n][k] = *(const PG8_LAS bf16x8*)(lds + PG8_SB(b, h) + boff + n * 2048 + k * 1024); } while (0)
; #define PG8_MMA(ai, bj, At, Bt) do { __builtin_amdgcn_s_setprio(1); _Pragma("unroll") for (int m = 0; m < 4; ++m) _Pragma("unroll") for (int n = 0; n < 2; ++n) _Pragma("unroll") for (int k = 0; k < 2; ++k) \
;         acc[ai][bj][m][n] = __builtin_amdgcn_mfma_f32_16x16x32_bf16(Bt[n][k], At[m][k], acc[ai][bj][m][n], 0, 0, 0); __builtin_amdgcn_s_setprio(0); } while (0)
; #define PG8_WAIT_V(n) asm volatile("s_waitcnt vmcnt(" #n ")" ::: "memory")
; #define PG8_WAIT_L(n) asm volatile("s_waitcnt lgkmcnt(" #n ")" ::: "memory")
; template <class Epi, class Sched, bool ALIGN_EPI = false, bool SP2 = false>
; __device__ __forceinline__ void gemm_phase(PG8_LAS unsigned char* lds, const Gemm g, const Sched& S, const Epi& E) {
;     ...
;             const bool last = (t == nt - 2);
;             const char* a1 = cA + (size_t)(t + 1) * kstep;
;             const char* a2 = last ? nA : cA + (size_t)(t + 2) * kstep; const char* b2 = last ? nB : cB + (size_t)(t + 2) * kstep;
;             const char* a3 = a2 + kstep; const char* b3 = b2 + kstep;
;             if (last && has_next) S.a_ready(nxt);
;             if constexpr (SP2) {
;             PG8_LDB(B0, 0, 0); PG8_LDB(B1, 0, 1); PG8_SCHED; PG8_LDA(At, 0, 0); PG8_STAGE(PG8_SA(1, 1), a1 + hstep, voffA);
;             PG8_WAIT_V(8); PG8_WAIT_L(0); PG8_BAR; PG8_MMA(0, 0, At, B0); PG8_MMA(0, 1, At, B1); PG8_BAR; PG8_SCHED;
;             PG8_LDA(At, 0, 1); PG8_STAGE(PG8_SB(0, 0), b2, voffB); PG8_STAGE(PG8_SB(0, 1), b2 + hstep, voffB); PG8_STAGE(PG8_SA(0, 0), a2, voffA);
;             PG8_WAIT_V(8); PG8_WAIT_L(0); PG8_BAR; PG8_MMA(1, 0, At, B0); PG8_MMA(1, 1, At, B1); PG8_BAR; PG8_SCHED;
.LBB0_383:
	s_add_i32 s73, s56, 2
	s_add_u32 s57, s44, s54
	s_addc_u32 s74, s45, s55
	s_add_u32 s75, s57, 0x100
	s_addc_u32 s57, s74, 0
	s_add_u32 s74, s47, s54
	s_addc_u32 s76, s49, s55
	s_add_i32 s77, 0, 0x10000
	s_cmp_eq_u32 s15, s56
	s_cselect_b32 s57, s5, s57
	s_cselect_b32 s56, s4, s75
	s_cselect_b32 s75, s43, s76
	s_cselect_b32 s74, s42, s74
	s_add_i32 s76, 0, 0x14000
	v_add_u32_e32 v146, s77, v209
	v_add_u32_e32 v188, s76, v209
	ds_read_b128 v[134:137], v146
	ds_read_b128 v[138:141], v146 offset:1024
	ds_read_b128 v[142:145], v146 offset:2048
	ds_read_b128 v[146:149], v146 offset:3072
	ds_read_b128 v[150:153], v188
	ds_read_b128 v[154:157], v188 offset:1024
	ds_read_b128 v[184:187], v188 offset:2048
	ds_read_b128 v[188:191], v188 offset:3072
	v_lshl_add_u64 v[200:201], v[130:131], 0, s[54:55]
	s_add_i32 m0, s58, 0xc000
	ds_read_b128 v[192:195], v211
	ds_read_b128 v[196:199], v211 offset:1024
	ds_read_b128 v[212:215], v211 offset:2048
	ds_read_b128 v[216:219], v211 offset:3072
	ds_read_b128 v[220:223], v211 offset:4096
	ds_read_b128 v[224:227], v211 offset:5120
	ds_read_b128 v[228:231], v211 offset:6144
	ds_read_b128 v[232:235], v211 offset:7168
	global_load_lds_dwordx4 v[200:201], off
	v_lshl_add_u64 v[200:201], v[132:133], 0, s[54:55]
	s_add_i32 m0, s58, 0xe000
	s_nop 0
	global_load_lds_dwordx4 v[200:201], off
	s_waitcnt vmcnt(8)
	s_waitcnt lgkmcnt(0)
	s_setprio 1
	s_barrier
	v_mfma_f32_16x16x32_bf16 v[126:129], v[134:137], v[192:195], v[126:129]
	v_mfma_f32_16x16x32_bf16 v[122:125], v[142:145], v[192:195], v[122:125]
	v_mfma_f32_16x16x32_bf16 v[110:113], v[134:137], v[212:215], v[110:113]
	v_mfma_f32_16x16x32_bf16 v[106:109], v[142:145], v[212:215], v[106:109]
	v_mfma_f32_16x16x32_bf16 v[94:97], v[134:137], v[220:223], v[94:97]
	v_mfma_f32_16x16x32_bf16 v[90:93], v[142:145], v[220:223], v[90:93]
	v_mfma_f32_16x16x32_bf16 v[76:79], v[134:137], v[228:231], v[76:79]
	v_mfma_f32_16x16x32_bf16 v[72:75], v[142:145], v[228:231], v[72:75]
	v_mfma_f32_16x16x32_bf16 v[126:129], v[138:141], v[196:199], v[126:129]
	v_mfma_f32_16x16x32_bf16 v[122:125], v[146:149], v[196:199], v[122:125]
	v_mfma_f32_16x16x32_bf16 v[110:113], v[138:141], v[216:219], v[110:113]
	v_mfma_f32_16x16x32_bf16 v[106:109], v[146:149], v[216:219], v[106:109]
	v_mfma_f32_16x16x32_bf16 v[94:97], v[138:141], v[224:227], v[94:97]
	v_mfma_f32_16x16x32_bf16 v[90:93], v[146:149], v[224:227], v[90:93]
	v_mfma_f32_16x16x32_bf16 v[76:79], v[138:141], v[232:235], v[76:79]
	v_mfma_f32_16x16x32_bf16 v[72:75], v[146:149], v[232:235], v[72:75]
	v_mfma_f32_16x16x32_bf16 v[118:121], v[150:153], v[192:195], v[118:121]
	v_mfma_f32_16x16x32_bf16 v[114:117], v[184:187], v[192:195], v[114:117]
	v_mfma_f32_16x16x32_bf16 v[102:105], v[150:153], v[212:215], v[102:105]
	v_mfma_f32_16x16x32_bf16 v[98:101], v[184:187], v[212:215], v[98:101]
	v_mfma_f32_16x16x32_bf16 v[86:89], v[150:153], v[220:223], v[86:89]
	v_mfma_f32_16x16x32_bf16 v[82:85], v[184:187], v[220:223], v[82:85]
	v_mfma_f32_16x16x32_bf16 v[68:71], v[150:153], v[228:231], v[68:71]
	v_mfma_f32_16x16x32_bf16 v[64:67], v[184:187], v[228:231], v[64:67]
	v_mfma_f32_16x16x32_bf16 v[118:121], v[154:157], v[196:199], v[118:121]
	v_mfma_f32_16x16x32_bf16 v[114:117], v[188:191], v[196:199], v[114:117]
	v_mfma_f32_16x16x32_bf16 v[102:105], v[154:157], v[216:219], v[102:105]
	v_mfma_f32_16x16x32_bf16 v[98:101], v[188:191], v[216:219], v[98:101]
	v_mfma_f32_16x16x32_bf16 v[86:89], v[154:157], v[224:227], v[86:89]
	v_mfma_f32_16x16x32_bf16 v[82:85], v[188:191], v[224:227], v[82:85]
	v_mfma_f32_16x16x32_bf16 v[68:71], v[154:157], v[232:235], v[68:71]
	v_mfma_f32_16x16x32_bf16 v[64:67], v[188:191], v[232:235], v[64:67]
	s_setprio 0
	s_barrier
	s_add_i32 s77, s77, s39
	v_lshl_add_u64 v[200:201], s[74:75], 0, v[176:177]
	s_mov_b32 m0, s77
	ds_read_b128 v[192:195], v211 offset:16384
	ds_read_b128 v[196:199], v211 offset:17408
	ds_read_b128 v[212:215], v211 offset:18432
	ds_read_b128 v[216:219], v211 offset:19456
	ds_read_b128 v[220:223], v211 offset:20480
	ds_read_b128 v[224:227], v211 offset:21504
	ds_read_b128 v[228:231], v211 offset:22528
	ds_read_b128 v[232:235], v211 offset:23552
	global_load_lds_dwordx4 v[200:201], off
	s_add_i32 m0, s77, 0x2000
	v_lshl_add_u64 v[236:237], s[74:75], 0, v[158:159]
	s_add_u32 s74, s74, s14
	s_addc_u32 s75, s75, 0
	s_add_i32 s76, s76, s39
	global_load_lds_dwordx4 v[236:237], off
	v_lshl_add_u64 v[238:239], s[74:75], 0, v[176:177]
	s_mov_b32 m0, s76
	v_lshl_add_u64 v[240:241], s[74:75], 0, v[158:159]
	global_load_lds_dwordx4 v[238:239], off
	s_add_i32 m0, s76, 0x2000
	v_lshl_add_u64 v[242:243], s[56:57], 0, v[178:179]
	global_load_lds_dwordx4 v[240:241], off
	s_mov_b32 m0, s58
	v_lshl_add_u64 v[244:245], s[56:57], 0, v[160:161]
	global_load_lds_dwordx4 v[242:243], off
	s_mov_b32 m0, s59
	s_nop 0
	global_load_lds_dwordx4 v[244:245], off
	s_waitcnt vmcnt(8)
	s_waitcnt lgkmcnt(0)
	s_setprio 1
	s_barrier
; #define PG8_STAGE(bufoff, gbase, voff) do { _Pragma("unroll") for (int _i = 0; _i < 2; ++_i) \
;         __builtin_amdgcn_global_load_lds((const unsigned*)((const char*)(gbase) + (voff)[_i]), (PG8_LAS unsigned*)(lds + (bufoff) + ldsw + _i * 8192), 16, 0, 0); } while (0)
; #define PG8_LDA(dst, b, h) do { _Pragma("unroll") for (int m = 0; m < 4; ++m) _Pragma("unroll") for (int k = 0; k < 2; ++k) dst[m][k] = *(const PG8_LAS bf16x8*)(lds + PG8_SA(b, h) + aoff + m * 2048 + k * 1024); } while (0)
; #define PG8_LDB(dst, b, h) do { _Pragma("unroll") for (int n = 0; n < 2; ++n) _Pragma("unroll") for (int k = 0; k < 2; ++k) dst[n][k] = *(const PG8_LAS bf16x8*)(lds + PG8_SB(b, h) + boff + n * 2048 + k * 1024); } while (0)
; #define PG8_MMA(ai, bj, At, Bt) do { __builtin_amdgcn_s_setprio(1); _Pragma("unroll") for (int m = 0; m < 4; ++m) _Pragma("unroll") for (int n = 0; n < 2; ++n) _Pragma("unroll") for (int k = 0; k < 2; ++k) \
;         acc[ai][bj][m][n] = __builtin_amdgcn_mfma_f32_16x16x32_bf16(Bt[n][k], At[m][k], acc[ai][bj][m][n], 0, 0, 0); __builtin_amdgcn_s_setprio(0); } while (0)
; #define PG8_WAIT_V(n) asm volatile("s_waitcnt vmcnt(" #n ")" ::: "memory")
; #define PG8_WAIT_L(n) asm volatile("s_waitcnt lgkmcnt(" #n ")" ::: "memory")
; #define PG8_BAR __builtin_amdgcn_s_barrier()
; #define PG8_SCHED __builtin_amdgcn_sched_barrier(0)
; template <class Epi, class Sched, bool ALIGN_EPI = false, bool SP2 = false>
; __device__ __forceinline__ void gemm_phase(PG8_LAS unsigned char* lds, const Gemm g, const Sched& S, const Epi& E) {
;     ...
;             PG8_WAIT_V(8); PG8_WAIT_L(0); PG8_BAR; PG8_MMA(1, 0, At, B0); PG8_MMA(1, 1, At, B1); PG8_BAR; PG8_SCHED;
;             PG8_LDB(B0, 1, 0); PG8_LDB(B1, 1, 1); PG8_SCHED; PG8_LDA(At, 1, 0); PG8_STAGE(PG8_SA(0, 1), a2 + hstep, voffA);
;             PG8_WAIT_V(8); PG8_WAIT_L(0); PG8_BAR; PG8_MMA(0, 0, At, B0); PG8_MMA(0, 1, At, B1); PG8_BAR; PG8_SCHED;
	v_mfma_f32_16x16x32_bf16 v[60:63], v[134:137], v[192:195], v[60:63]
	v_mfma_f32_16x16x32_bf16 v[56:59], v[142:145], v[192:195], v[56:59]
	v_mfma_f32_16x16x32_bf16 v[44:47], v[134:137], v[212:215], v[44:47]
	v_mfma_f32_16x16x32_bf16 v[40:43], v[142:145], v[212:215], v[40:43]
	v_mfma_f32_16x16x32_bf16 v[28:31], v[134:137], v[220:223], v[28:31]
	v_mfma_f32_16x16x32_bf16 v[24:27], v[142:145], v[220:223], v[24:27]
	v_mfma_f32_16x16x32_bf16 v[12:15], v[134:137], v[228:231], v[12:15]
	v_mfma_f32_16x16x32_bf16 v[8:11], v[142:145], v[228:231], v[8:11]
	v_mfma_f32_16x16x32_bf16 v[60:63], v[138:141], v[196:199], v[60:63]
	v_mfma_f32_16x16x32_bf16 v[56:59], v[146:149], v[196:199], v[56:59]
	v_mfma_f32_16x16x32_bf16 v[44:47], v[138:141], v[216:219], v[44:47]
	v_mfma_f32_16x16x32_bf16 v[40:43], v[146:149], v[216:219], v[40:43]
	v_mfma_f32_16x16x32_bf16 v[28:31], v[138:141], v[224:227], v[28:31]
	v_mfma_f32_16x16x32_bf16 v[24:27], v[146:149], v[224:227], v[24:27]
	v_mfma_f32_16x16x32_bf16 v[12:15], v[138:141], v[232:235], v[12:15]
	v_mfma_f32_16x16x32_bf16 v[8:11], v[146:149], v[232:235], v[8:11]
	v_mfma_f32_16x16x32_bf16 v[52:55], v[150:153], v[192:195], v[52:55]
	v_mfma_f32_16x16x32_bf16 v[48:51], v[184:187], v[192:195], v[48:51]
	v_mfma_f32_16x16x32_bf16 v[36:39], v[150:153], v[212:215], v[36:39]
	v_mfma_f32_16x16x32_bf16 v[32:35], v[184:187], v[212:215], v[32:35]
	v_mfma_f32_16x16x32_bf16 v[20:23], v[150:153], v[220:223], v[20:23]
	v_mfma_f32_16x16x32_bf16 v[16:19], v[184:187], v[220:223], v[16:19]
	v_mfma_f32_16x16x32_bf16 v[4:7], v[150:153], v[228:231], v[4:7]
	v_mfma_f32_16x16x32_bf16 v[0:3], v[184:187], v[228:231], v[0:3]
	v_mfma_f32_16x16x32_bf16 v[52:55], v[154:157], v[196:199], v[52:55]
	v_mfma_f32_16x16x32_bf16 v[48:51], v[188:191], v[196:199], v[48:51]
	v_mfma_f32_16x16x32_bf16 v[36:39], v[154:157], v[216:219], v[36:39]
	v_mfma_f32_16x16x32_bf16 v[32:35], v[188:191], v[216:219], v[32:35]
	v_mfma_f32_16x16x32_bf16 v[20:23], v[154:157], v[224:227], v[20:23]
	v_mfma_f32_16x16x32_bf16 v[16:19], v[188:191], v[224:227], v[16:19]
	v_mfma_f32_16x16x32_bf16 v[4:7], v[154:157], v[232:235], v[4:7]
	v_mfma_f32_16x16x32_bf16 v[0:3], v[188:191], v[232:235], v[0:3]
	s_setprio 0
	s_barrier
	s_add_i32 s74, 0, 0x18000
	s_add_i32 s75, 0, 0x1c000
	v_add_u32_e32 v146, s74, v209
	v_add_u32_e32 v188, s75, v209
	ds_read_b128 v[134:137], v146
	ds_read_b128 v[138:141], v146 offset:1024
	ds_read_b128 v[142:145], v146 offset:2048
	ds_read_b128 v[146:149], v146 offset:3072
	ds_read_b128 v[150:153], v188
	ds_read_b128 v[154:157], v188 offset:1024
	ds_read_b128 v[184:187], v188 offset:2048
	ds_read_b128 v[188:191], v188 offset:3072
	s_add_u32 s56, s56, s14
	s_addc_u32 s57, s57, 0
	s_mov_b32 m0, s60
	v_lshl_add_u64 v[246:247], s[56:57], 0, v[178:179]
	ds_read_b128 v[192:195], v211 offset:32768
	ds_read_b128 v[196:199], v211 offset:33792
	ds_read_b128 v[212:215], v211 offset:34816
	ds_read_b128 v[216:219], v211 offset:35840
	ds_read_b128 v[220:223], v211 offset:36864
	ds_read_b128 v[224:227], v211 offset:37888
	ds_read_b128 v[228:231], v211 offset:38912
	ds_read_b128 v[232:235], v211 offset:39936
	global_load_lds_dwordx4 v[246:247], off
	v_lshl_add_u64 v[246:247], s[56:57], 0, v[160:161]
	s_mov_b32 m0, s61
	s_nop 0
	global_load_lds_dwordx4 v[246:247], off
	s_waitcnt vmcnt(8)
	s_waitcnt lgkmcnt(0)
	s_setprio 1
	s_barrier
	v_mfma_f32_16x16x32_bf16 v[126:129], v[134:137], v[192:195], v[126:129]
	v_mfma_f32_16x16x32_bf16 v[122:125], v[142:145], v[192:195], v[122:125]
	v_mfma_f32_16x16x32_bf16 v[110:113], v[134:137], v[212:215], v[110:113]
	v_mfma_f32_16x16x32_bf16 v[106:109], v[142:145], v[212:215], v[106:109]
	v_mfma_f32_16x16x32_bf16 v[94:97], v[134:137], v[220:223], v[94:97]
	v_mfma_f32_16x16x32_bf16 v[90:93], v[142:145], v[220:223], v[90:93]
	v_mfma_f32_16x16x32_bf16 v[76:79], v[134:137], v[228:231], v[76:79]
	v_mfma_f32_16x16x32_bf16 v[72:75], v[142:145], v[228:231], v[72:75]
	v_mfma_f32_16x16x32_bf16 v[126:129], v[138:141], v[196:199], v[126:129]
	v_mfma_f32_16x16x32_bf16 v[122:125], v[146:149], v[196:199], v[122:125]
	v_mfma_f32_16x16x32_bf16 v[110:113], v[138:141], v[216:219], v[110:113]
	v_mfma_f32_16x16x32_bf16 v[106:109], v[146:149], v[216:219], v[106:109]
	v_mfma_f32_16x16x32_bf16 v[94:97], v[138:141], v[224:227], v[94:97]
	v_mfma_f32_16x16x32_bf16 v[90:93], v[146:149], v[224:227], v[90:93]
	v_mfma_f32_16x16x32_bf16 v[76:79], v[138:141], v[232:235], v[76:79]
	v_mfma_f32_16x16x32_bf16 v[72:75], v[146:149], v[232:235], v[72:75]
	v_mfma_f32_16x16x32_bf16 v[118:121], v[150:153], v[192:195], v[118:121]
	v_mfma_f32_16x16x32_bf16 v[114:117], v[184:187], v[192:195], v[114:117]
	v_mfma_f32_16x16x32_bf16 v[102:105], v[150:153], v[212:215], v[102:105]
	v_mfma_f32_16x16x32_bf16 v[98:101], v[184:187], v[212:215], v[98:101]
	v_mfma_f32_16x16x32_bf16 v[86:89], v[150:153], v[220:223], v[86:89]
	v_mfma_f32_16x16x32_bf16 v[82:85], v[184:187], v[220:223], v[82:85]
	v_mfma_f32_16x16x32_bf16 v[68:71], v[150:153], v[228:231], v[68:71]
	v_mfma_f32_16x16x32_bf16 v[64:67], v[184:187], v[228:231], v[64:67]
	v_mfma_f32_16x16x32_bf16 v[118:121], v[154:157], v[196:199], v[118:121]
	v_mfma_f32_16x16x32_bf16 v[114:117], v[188:191], v[196:199], v[114:117]
	v_mfma_f32_16x16x32_bf16 v[102:105], v[154:157], v[216:219], v[102:105]
	v_mfma_f32_16x16x32_bf16 v[98:101], v[188:191], v[216:219], v[98:101]
	v_mfma_f32_16x16x32_bf16 v[86:89], v[154:157], v[224:227], v[86:89]
	v_mfma_f32_16x16x32_bf16 v[82:85], v[188:191], v[224:227], v[82:85]
	v_mfma_f32_16x16x32_bf16 v[68:71], v[154:157], v[232:235], v[68:71]
	v_mfma_f32_16x16x32_bf16 v[64:67], v[188:191], v[232:235], v[64:67]
	s_setprio 0
	s_barrier
; #define PG8_STAGE(bufoff, gbase, voff) do { _Pragma("unroll") for (int _i = 0; _i < 2; ++_i) \
;         __builtin_amdgcn_global_load_lds((const unsigned*)((const char*)(gbase) + (voff)[_i]), (PG8_LAS unsigned*)(lds + (bufoff) + ldsw + _i * 8192), 16, 0, 0); } while (0)
; #define PG8_LDA(dst, b, h) do { _Pragma("unroll") for (int m = 0; m < 4; ++m) _Pragma("unroll") for (int k = 0; k < 2; ++k) dst[m][k] = *(const PG8_LAS bf16x8*)(lds + PG8_SA(b, h) + aoff + m * 2048 + k * 1024); } while (0)
; #define PG8_MMA(ai, bj, At, Bt) do { __builtin_amdgcn_s_setprio(1); _Pragma("unroll") for (int m = 0; m < 4; ++m) _Pragma("unroll") for (int n = 0; n < 2; ++n) _Pragma("unroll") for (int k = 0; k < 2; ++k) \
;         acc[ai][bj][m][n] = __builtin_amdgcn_mfma_f32_16x16x32_bf16(Bt[n][k], At[m][k], acc[ai][bj][m][n], 0, 0, 0); __builtin_amdgcn_s_setprio(0); } while (0)
; #define PG8_WAIT_V(n) asm volatile("s_waitcnt vmcnt(" #n ")" ::: "memory")
; #define PG8_WAIT_L(n) asm volatile("s_waitcnt lgkmcnt(" #n ")" ::: "memory")
; #define PG8_BAR __builtin_amdgcn_s_barrier()
; #define PG8_SCHED __builtin_amdgcn_sched_barrier(0)
; template <class Epi, class Sched, bool ALIGN_EPI = false, bool SP2 = false>
; __device__ __forceinline__ void gemm_phase(PG8_LAS unsigned char* lds, const Gemm g, const Sched& S, const Epi& E) {
;     ...
;         for (int t = 0; t < nt; t += 2) {
;     ...
;             PG8_LDA(At, 1, 1); PG8_STAGE(PG8_SB(1, 0), b3, voffB); PG8_STAGE(PG8_SB(1, 1), b3 + hstep, voffB); PG8_STAGE(PG8_SA(1, 0), a3, voffA);
;             PG8_WAIT_V(8); PG8_WAIT_L(0); PG8_BAR; PG8_MMA(1, 0, At, B0); PG8_MMA(1, 1, At, B1); PG8_BAR; PG8_SCHED;
	s_add_i32 s56, s74, s39
	v_lshl_add_u64 v[200:201], v[200:201], 0, s[40:41]
	s_mov_b32 m0, s56
	ds_read_b128 v[192:195], v211 offset:49152
	ds_read_b128 v[196:199], v211 offset:50176
	ds_read_b128 v[212:215], v211 offset:51200
	ds_read_b128 v[216:219], v211 offset:52224
	ds_read_b128 v[220:223], v211 offset:53248
	ds_read_b128 v[224:227], v211 offset:54272
	ds_read_b128 v[228:231], v211 offset:55296
	ds_read_b128 v[232:235], v211 offset:56320
	global_load_lds_dwordx4 v[200:201], off
	v_lshl_add_u64 v[200:201], v[236:237], 0, s[40:41]
	s_add_i32 m0, s56, 0x2000
	s_add_i32 s56, s75, s39
	global_load_lds_dwordx4 v[200:201], off
	v_lshl_add_u64 v[200:201], v[238:239], 0, s[40:41]
	s_mov_b32 m0, s56
	s_nop 0
	global_load_lds_dwordx4 v[200:201], off
	v_lshl_add_u64 v[200:201], v[240:241], 0, s[40:41]
	s_add_i32 m0, s56, 0x2000
	s_nop 0
	global_load_lds_dwordx4 v[200:201], off
	v_lshl_add_u64 v[200:201], v[242:243], 0, s[40:41]
	s_mov_b32 m0, s66
	s_nop 0
	global_load_lds_dwordx4 v[200:201], off
	v_lshl_add_u64 v[200:201], v[244:245], 0, s[40:41]
	s_mov_b32 m0, s67
	s_nop 0
	global_load_lds_dwordx4 v[200:201], off
	s_waitcnt vmcnt(8)
	s_waitcnt lgkmcnt(0)
	s_setprio 1
	s_barrier
	v_mfma_f32_16x16x32_bf16 v[60:63], v[134:137], v[192:195], v[60:63]
	v_mfma_f32_16x16x32_bf16 v[56:59], v[142:145], v[192:195], v[56:59]
	v_mfma_f32_16x16x32_bf16 v[44:47], v[134:137], v[212:215], v[44:47]
	v_mfma_f32_16x16x32_bf16 v[40:43], v[142:145], v[212:215], v[40:43]
	v_mfma_f32_16x16x32_bf16 v[28:31], v[134:137], v[220:223], v[28:31]
	v_mfma_f32_16x16x32_bf16 v[24:27], v[142:145], v[220:223], v[24:27]
	v_mfma_f32_16x16x32_bf16 v[12:15], v[134:137], v[228:231], v[12:15]
	v_mfma_f32_16x16x32_bf16 v[8:11], v[142:145], v[228:231], v[8:11]
	v_mfma_f32_16x16x32_bf16 v[60:63], v[138:141], v[196:199], v[60:63]
	v_mfma_f32_16x16x32_bf16 v[56:59], v[146:149], v[196:199], v[56:59]
	v_mfma_f32_16x16x32_bf16 v[44:47], v[138:141], v[216:219], v[44:47]
	v_mfma_f32_16x16x32_bf16 v[40:43], v[146:149], v[216:219], v[40:43]
	v_mfma_f32_16x16x32_bf16 v[28:31], v[138:141], v[224:227], v[28:31]
	v_mfma_f32_16x16x32_bf16 v[24:27], v[146:149], v[224:227], v[24:27]
	v_mfma_f32_16x16x32_bf16 v[12:15], v[138:141], v[232:235], v[12:15]
	v_mfma_f32_16x16x32_bf16 v[8:11], v[146:149], v[232:235], v[8:11]
	v_mfma_f32_16x16x32_bf16 v[52:55], v[150:153], v[192:195], v[52:55]
	v_mfma_f32_16x16x32_bf16 v[48:51], v[184:187], v[192:195], v[48:51]
	v_mfma_f32_16x16x32_bf16 v[36:39], v[150:153], v[212:215], v[36:39]
	v_mfma_f32_16x16x32_bf16 v[32:35], v[184:187], v[212:215], v[32:35]
	v_mfma_f32_16x16x32_bf16 v[20:23], v[150:153], v[220:223], v[20:23]
	v_mfma_f32_16x16x32_bf16 v[16:19], v[184:187], v[220:223], v[16:19]
	v_mfma_f32_16x16x32_bf16 v[4:7], v[150:153], v[228:231], v[4:7]
	v_mfma_f32_16x16x32_bf16 v[0:3], v[184:187], v[228:231], v[0:3]
	v_mfma_f32_16x16x32_bf16 v[52:55], v[154:157], v[196:199], v[52:55]
	v_mfma_f32_16x16x32_bf16 v[48:51], v[188:191], v[196:199], v[48:51]
	v_mfma_f32_16x16x32_bf16 v[36:39], v[154:157], v[216:219], v[36:39]
	v_mfma_f32_16x16x32_bf16 v[32:35], v[188:191], v[216:219], v[32:35]
	v_mfma_f32_16x16x32_bf16 v[20:23], v[154:157], v[224:227], v[20:23]
	v_mfma_f32_16x16x32_bf16 v[16:19], v[188:191], v[224:227], v[16:19]
	v_mfma_f32_16x16x32_bf16 v[4:7], v[154:157], v[232:235], v[4:7]
	v_mfma_f32_16x16x32_bf16 v[0:3], v[188:191], v[232:235], v[0:3]
	s_setprio 0
	s_barrier
	s_add_u32 s54, s54, 0x100
	s_addc_u32 s55, s55, 0
	s_cmp_ge_u32 s73, s63
	s_mov_b32 s56, s73
	s_cbranch_scc1 .LBB0_386
